# norm phases: gamma/shift/scale loads hoisted and prefetched 4 steps ahead with counted vmcnt (no per-step drain of stores)
# speedup vs baseline: 1.0008x; 1.0008x over previous
.LBB0_262:
	v_lshl_add_u64 v[0:1], s[16:17], 0, v[18:19]
	v_add_co_u32_e32 v0, vcc, 0x3000000, v0
	s_waitcnt vmcnt(12)
	v_lshl_add_u64 v[36:37], s[12:13], 0, v[18:19]
	v_addc_co_u32_e32 v1, vcc, 0, v1, vcc
	global_load_dwordx2 v[2:3], v[0:1], off
	global_load_dwordx2 v[4:5], v[0:1], off offset:512
	global_load_dwordx2 v[6:7], v[0:1], off offset:1024
	global_load_dwordx2 v[28:29], v[0:1], off offset:1536
	global_load_dwordx2 v[30:31], v[0:1], off offset:2048
	global_load_dwordx2 v[32:33], v[0:1], off offset:2560
	global_load_dwordx2 v[34:35], v[0:1], off offset:3072
	s_nop 0
	global_load_dwordx2 v[0:1], v[0:1], off offset:3584
	v_add_co_u32_e32 v36, vcc, 0x3000000, v36
	s_add_i32 s18, s4, 2
	s_nop 0
	v_addc_co_u32_e32 v37, vcc, 0, v37, vcc
	global_load_dwordx2 v[38:39], v[36:37], off
	global_load_dwordx2 v[40:41], v[36:37], off offset:512
	global_load_dwordx2 v[42:43], v[36:37], off offset:1024
	global_load_dwordx2 v[46:47], v[36:37], off offset:1536
	global_load_dwordx2 v[48:49], v[36:37], off offset:2048
	global_load_dwordx2 v[50:51], v[36:37], off offset:2560
	global_load_dwordx2 v[52:53], v[36:37], off offset:3072
	s_nop 0
	global_load_dwordx2 v[36:37], v[36:37], off offset:3584
	s_ashr_i32 s19, s18, 31
	s_add_i32 s22, s4, 3
	s_lshl_b64 s[18:19], s[18:19], 12
	s_ashr_i32 s23, s22, 31
	v_lshl_add_u64 v[56:57], v[20:21], 0, s[18:19]
	s_lshl_b64 s[22:23], s[22:23], 12
	global_load_dwordx2 v[68:69], v[56:57], off
	global_load_dwordx2 v[70:71], v[56:57], off offset:512
	global_load_dwordx2 v[72:73], v[56:57], off offset:1024
	global_load_dwordx2 v[74:75], v[56:57], off offset:1536
	global_load_dwordx2 v[94:95], v[56:57], off offset:2048
	global_load_dwordx2 v[96:97], v[56:57], off offset:2560
	global_load_dwordx2 v[98:99], v[56:57], off offset:3072
	global_load_dwordx2 v[106:107], v[56:57], off offset:3584
	v_lshl_add_u64 v[56:57], v[20:21], 0, s[22:23]
	global_load_dwordx2 v[128:129], v[56:57], off
	global_load_dwordx2 v[130:131], v[56:57], off offset:512
	global_load_dwordx2 v[146:147], v[56:57], off offset:1024
	global_load_dwordx2 v[164:165], v[56:57], off offset:1536
	global_load_dwordx2 v[166:167], v[56:57], off offset:2048
	global_load_dwordx2 v[168:169], v[56:57], off offset:2560
	global_load_dwordx2 v[170:171], v[56:57], off offset:3072
	global_load_dwordx2 v[176:177], v[56:57], off offset:3584
	s_ashr_i32 s5, s4, 31
	s_lshr_b32 s5, s5, 20
	s_add_i32 s5, s4, s5
	s_ashr_i32 s5, s5, 12
	v_mad_i64_i32 v[230:231], vcc, s5, v237, v[22:23]
	v_mad_i64_i32 v[192:193], vcc, s5, v237, v[24:25]
	v_lshl_add_u64 v[250:251], v[230:231], 0, s[86:87]
	v_lshl_add_u64 v[252:253], v[192:193], 0, s[86:87]
	global_load_dwordx4 v[180:183], v[8:9], off
	global_load_dwordx4 v[184:187], v[230:231], off
	global_load_dwordx4 v[188:191], v[192:193], off
	global_load_dwordx4 v[196:199], v[8:9], off offset:1024
	global_load_dwordx4 v[200:203], v[230:231], off offset:1024
	global_load_dwordx4 v[204:207], v[192:193], off offset:1024
	global_load_dwordx4 v[208:211], v[8:9], off offset:2048
	global_load_dwordx4 v[212:215], v[230:231], off offset:2048
	global_load_dwordx4 v[218:221], v[192:193], off offset:2048
	global_load_dwordx4 v[222:225], v[8:9], off offset:3072
	global_load_dwordx4 v[226:229], v[230:231], off offset:3072
	global_load_dwordx4 v[242:245], v[192:193], off offset:3072
	s_add_i32 s4, s4, s6
	s_cmp_lt_i32 s4, s20
	s_waitcnt vmcnt(43)
	v_cvt_f32_f16_sdwa v163, v2 dst_sel:DWORD dst_unused:UNUSED_PAD src0_sel:WORD_1
	s_waitcnt vmcnt(42)
	v_cvt_f32_f16_sdwa v135, v4 dst_sel:DWORD dst_unused:UNUSED_PAD src0_sel:WORD_1
	v_cvt_f32_f16_sdwa v101, v3 dst_sel:DWORD dst_unused:UNUSED_PAD src0_sel:WORD_1
	v_cvt_f32_f16_e32 v162, v2
	v_cvt_f32_f16_sdwa v133, v5 dst_sel:DWORD dst_unused:UNUSED_PAD src0_sel:WORD_1
	v_cvt_f32_f16_e32 v134, v4
	v_cvt_f32_f16_e32 v100, v3
	v_cvt_f32_f16_e32 v132, v5
	s_waitcnt vmcnt(41)
	v_cvt_f32_f16_e32 v116, v6
	v_cvt_f32_f16_sdwa v117, v6 dst_sel:DWORD dst_unused:UNUSED_PAD src0_sel:WORD_1
	v_cvt_f32_f16_e32 v118, v7
	v_cvt_f32_f16_sdwa v119, v7 dst_sel:DWORD dst_unused:UNUSED_PAD src0_sel:WORD_1
	v_mov_b32_e32 v2, v163
	v_mov_b32_e32 v3, v135
	s_waitcnt vmcnt(40)
	v_cvt_f32_f16_e32 v108, v28
	v_cvt_f32_f16_sdwa v109, v28 dst_sel:DWORD dst_unused:UNUSED_PAD src0_sel:WORD_1
	v_cvt_f32_f16_e32 v110, v29
	v_cvt_f32_f16_sdwa v111, v29 dst_sel:DWORD dst_unused:UNUSED_PAD src0_sel:WORD_1
	s_waitcnt vmcnt(39)
	v_cvt_f32_f16_sdwa v87, v31 dst_sel:DWORD dst_unused:UNUSED_PAD src0_sel:WORD_1
	v_cvt_f32_f16_e32 v86, v31
	v_cvt_f32_f16_sdwa v85, v30 dst_sel:DWORD dst_unused:UNUSED_PAD src0_sel:WORD_1
	v_cvt_f32_f16_e32 v84, v30
	s_waitcnt vmcnt(36)
	v_cvt_f32_f16_sdwa v29, v1 dst_sel:DWORD dst_unused:UNUSED_PAD src0_sel:WORD_1
	v_cvt_f32_f16_e32 v28, v1
	v_cvt_f32_f16_sdwa v31, v0 dst_sel:DWORD dst_unused:UNUSED_PAD src0_sel:WORD_1
	v_cvt_f32_f16_e32 v30, v0
	v_mov_b32_e32 v0, v162
	v_mov_b32_e32 v1, v134
	v_pk_mul_f32 v[2:3], v[2:3], v[2:3]
	v_mov_b32_e32 v4, v101
	v_mov_b32_e32 v5, v133
	v_pk_fma_f32 v[0:1], v[0:1], v[0:1], v[2:3]
	v_mov_b32_e32 v2, v100
	v_mov_b32_e32 v3, v132
	v_pk_mul_f32 v[4:5], v[4:5], v[4:5]
	v_cvt_f32_f16_e32 v80, v32
	v_pk_fma_f32 v[2:3], v[2:3], v[2:3], v[4:5]
	v_pk_mul_f32 v[4:5], v[116:117], v[116:117]
	v_pk_add_f32 v[0:1], v[0:1], v[2:3]
	v_pk_mul_f32 v[2:3], v[118:119], v[118:119]
	v_pk_add_f32 v[0:1], v[0:1], v[0:1] op_sel:[0,1] op_sel_hi:[1,0]
	v_pk_mov_b32 v[6:7], v[4:5], v[2:3] op_sel:[1,0]
	v_mov_b32_e32 v5, v3
	v_pk_add_f32 v[2:3], v[6:7], v[4:5]
	v_mul_f32_e32 v4, v84, v84
	v_mul_f32_e32 v5, v85, v85
	v_pk_add_f32 v[2:3], v[2:3], v[2:3] op_sel:[0,1] op_sel_hi:[1,0]
	v_mov_b32_e32 v1, v4
	v_mov_b32_e32 v3, v5
	v_cvt_f32_f16_sdwa v81, v32 dst_sel:DWORD dst_unused:UNUSED_PAD src0_sel:WORD_1
	v_cvt_f32_f16_e32 v82, v33
	v_cvt_f32_f16_sdwa v83, v33 dst_sel:DWORD dst_unused:UNUSED_PAD src0_sel:WORD_1
	v_pk_add_f32 v[0:1], v[0:1], v[2:3]
	v_mul_f32_e32 v2, v109, v109
	v_mul_f32_e32 v4, v111, v111
	v_mul_f32_e32 v6, v86, v86
	v_mul_f32_e32 v7, v87, v87
	v_pk_fma_f32 v[2:3], v[108:109], v[108:109], v[2:3] op_sel_hi:[1,1,0]
	v_pk_fma_f32 v[4:5], v[110:111], v[110:111], v[4:5] op_sel_hi:[1,1,0]
	v_mov_b32_e32 v3, v6
	v_mov_b32_e32 v5, v7
	v_pk_add_f32 v[2:3], v[2:3], v[4:5]
	v_pk_mul_f32 v[4:5], v[80:81], v[80:81]
	v_pk_add_f32 v[0:1], v[0:1], v[2:3]
	v_pk_mul_f32 v[2:3], v[82:83], v[82:83]
	v_cvt_f32_f16_sdwa v57, v34 dst_sel:DWORD dst_unused:UNUSED_PAD src0_sel:WORD_1
	v_cvt_f32_f16_sdwa v59, v35 dst_sel:DWORD dst_unused:UNUSED_PAD src0_sel:WORD_1
	v_pk_mov_b32 v[6:7], v[4:5], v[2:3] op_sel:[1,0]
	v_mov_b32_e32 v5, v3
	v_cvt_f32_f16_e32 v56, v34
	v_cvt_f32_f16_e32 v58, v35
	v_pk_add_f32 v[2:3], v[6:7], v[4:5]
	v_mul_f32_e32 v4, v30, v30
	v_mul_f32_e32 v5, v31, v31
	v_pk_add_f32 v[0:1], v[0:1], v[0:1] op_sel:[0,1] op_sel_hi:[1,0]
	v_pk_add_f32 v[2:3], v[2:3], v[2:3] op_sel:[0,1] op_sel_hi:[1,0]
	v_mov_b32_e32 v1, v4
	v_mov_b32_e32 v3, v5
	v_pk_add_f32 v[0:1], v[0:1], v[2:3]
	v_mul_f32_e32 v2, v57, v57
	v_mul_f32_e32 v4, v59, v59
	v_mul_f32_e32 v6, v28, v28
	v_mul_f32_e32 v7, v29, v29
	v_pk_fma_f32 v[2:3], v[56:57], v[56:57], v[2:3] op_sel_hi:[1,1,0]
	v_pk_fma_f32 v[4:5], v[58:59], v[58:59], v[4:5] op_sel_hi:[1,1,0]
	v_mov_b32_e32 v3, v6
	v_mov_b32_e32 v5, v7
	v_pk_add_f32 v[2:3], v[2:3], v[4:5]
	s_waitcnt vmcnt(35)
	v_cvt_f32_f16_sdwa v161, v38 dst_sel:DWORD dst_unused:UNUSED_PAD src0_sel:WORD_1
	v_pk_add_f32 v[0:1], v[0:1], v[2:3]
	s_waitcnt vmcnt(34)
	v_cvt_f32_f16_sdwa v143, v40 dst_sel:DWORD dst_unused:UNUSED_PAD src0_sel:WORD_1
	v_add_f32_e32 v0, v0, v1
	ds_bpermute_b32 v1, v45, v0
	v_cvt_f32_f16_sdwa v103, v39 dst_sel:DWORD dst_unused:UNUSED_PAD src0_sel:WORD_1
	v_cvt_f32_f16_e32 v160, v38
	v_cvt_f32_f16_sdwa v141, v41 dst_sel:DWORD dst_unused:UNUSED_PAD src0_sel:WORD_1
	v_cvt_f32_f16_e32 v142, v40
	s_waitcnt lgkmcnt(0)
	v_add_f32_e32 v0, v0, v1
	ds_bpermute_b32 v1, v55, v0
	v_cvt_f32_f16_e32 v102, v39
	v_cvt_f32_f16_e32 v140, v41
	s_waitcnt vmcnt(33)
	v_cvt_f32_f16_e32 v124, v42
	v_cvt_f32_f16_sdwa v125, v42 dst_sel:DWORD dst_unused:UNUSED_PAD src0_sel:WORD_1
	s_waitcnt lgkmcnt(0)
	v_add_f32_e32 v0, v0, v1
	ds_bpermute_b32 v1, v65, v0
	v_cvt_f32_f16_e32 v126, v43
	v_cvt_f32_f16_sdwa v127, v43 dst_sel:DWORD dst_unused:UNUSED_PAD src0_sel:WORD_1
	v_mov_b32_e32 v2, v161
	v_mov_b32_e32 v3, v143
	s_waitcnt lgkmcnt(0)
	v_add_f32_e32 v0, v0, v1
	ds_bpermute_b32 v1, v67, v0
	v_pk_mul_f32 v[2:3], v[2:3], v[2:3]
	v_mov_b32_e32 v4, v103
	v_mov_b32_e32 v5, v141
	v_pk_mul_f32 v[4:5], v[4:5], v[4:5]
	s_waitcnt lgkmcnt(0)
	v_add_f32_e32 v0, v0, v1
	ds_bpermute_b32 v1, v172, v0
	s_waitcnt vmcnt(31)
	v_cvt_f32_f16_sdwa v91, v48 dst_sel:DWORD dst_unused:UNUSED_PAD src0_sel:WORD_1
	v_cvt_f32_f16_e32 v90, v48
	v_cvt_f32_f16_sdwa v113, v46 dst_sel:DWORD dst_unused:UNUSED_PAD src0_sel:WORD_1
	v_cvt_f32_f16_sdwa v115, v47 dst_sel:DWORD dst_unused:UNUSED_PAD src0_sel:WORD_1
	s_waitcnt lgkmcnt(0)
	v_add_f32_e32 v0, v0, v1
	ds_bpermute_b32 v1, v173, v0
	v_cvt_f32_f16_e32 v112, v46
	v_cvt_f32_f16_e32 v114, v47
	v_cvt_f32_f16_sdwa v89, v49 dst_sel:DWORD dst_unused:UNUSED_PAD src0_sel:WORD_1
	v_cvt_f32_f16_e32 v88, v49
	s_waitcnt lgkmcnt(0)
	v_add_f32_e32 v0, v0, v1
	v_fmamk_f32 v0, v0, 0x3a000000, v232
	v_rsq_f32_e32 v44, v0
	v_mov_b32_e32 v0, v160
	v_mov_b32_e32 v1, v142
	v_pk_fma_f32 v[0:1], v[0:1], v[0:1], v[2:3]
	v_mov_b32_e32 v2, v102
	v_mov_b32_e32 v3, v140
	v_pk_fma_f32 v[2:3], v[2:3], v[2:3], v[4:5]
	v_pk_mul_f32 v[4:5], v[124:125], v[124:125]
	v_pk_add_f32 v[0:1], v[0:1], v[2:3]
	v_pk_mul_f32 v[2:3], v[126:127], v[126:127]
	v_pk_add_f32 v[0:1], v[0:1], v[0:1] op_sel:[0,1] op_sel_hi:[1,0]
	v_pk_mov_b32 v[6:7], v[4:5], v[2:3] op_sel:[1,0]
	v_mov_b32_e32 v5, v3
	v_pk_add_f32 v[2:3], v[6:7], v[4:5]
	v_mul_f32_e32 v4, v90, v90
	v_mul_f32_e32 v5, v91, v91
	v_pk_add_f32 v[2:3], v[2:3], v[2:3] op_sel:[0,1] op_sel_hi:[1,0]
	v_mov_b32_e32 v1, v4
	v_mov_b32_e32 v3, v5
	s_waitcnt vmcnt(30)
	v_cvt_f32_f16_e32 v76, v50
	v_cvt_f32_f16_sdwa v77, v50 dst_sel:DWORD dst_unused:UNUSED_PAD src0_sel:WORD_1
	v_cvt_f32_f16_e32 v78, v51
	v_cvt_f32_f16_sdwa v79, v51 dst_sel:DWORD dst_unused:UNUSED_PAD src0_sel:WORD_1
	v_pk_add_f32 v[0:1], v[0:1], v[2:3]
	v_mul_f32_e32 v2, v113, v113
	v_mul_f32_e32 v4, v115, v115
	v_mul_f32_e32 v6, v88, v88
	v_mul_f32_e32 v7, v89, v89
	v_pk_fma_f32 v[2:3], v[112:113], v[112:113], v[2:3] op_sel_hi:[1,1,0]
	v_pk_fma_f32 v[4:5], v[114:115], v[114:115], v[4:5] op_sel_hi:[1,1,0]
	v_mov_b32_e32 v3, v6
	v_mov_b32_e32 v5, v7
	s_waitcnt vmcnt(28)
	v_cvt_f32_f16_sdwa v35, v36 dst_sel:DWORD dst_unused:UNUSED_PAD src0_sel:WORD_1
	v_cvt_f32_f16_e32 v34, v36
	v_pk_add_f32 v[2:3], v[2:3], v[4:5]
	v_pk_mul_f32 v[4:5], v[76:77], v[76:77]
	v_pk_add_f32 v[0:1], v[0:1], v[2:3]
	v_pk_mul_f32 v[2:3], v[78:79], v[78:79]
	v_cvt_f32_f16_sdwa v61, v52 dst_sel:DWORD dst_unused:UNUSED_PAD src0_sel:WORD_1
	v_cvt_f32_f16_sdwa v63, v53 dst_sel:DWORD dst_unused:UNUSED_PAD src0_sel:WORD_1
	v_pk_mov_b32 v[6:7], v[4:5], v[2:3] op_sel:[1,0]
	v_mov_b32_e32 v5, v3
	v_cvt_f32_f16_e32 v60, v52
	v_cvt_f32_f16_e32 v62, v53
	v_cvt_f32_f16_sdwa v33, v37 dst_sel:DWORD dst_unused:UNUSED_PAD src0_sel:WORD_1
	v_cvt_f32_f16_e32 v32, v37
	v_pk_add_f32 v[2:3], v[6:7], v[4:5]
	v_mul_f32_e32 v4, v34, v34
	v_mul_f32_e32 v5, v35, v35
	v_pk_add_f32 v[0:1], v[0:1], v[0:1] op_sel:[0,1] op_sel_hi:[1,0]
	v_pk_add_f32 v[2:3], v[2:3], v[2:3] op_sel:[0,1] op_sel_hi:[1,0]
	v_mov_b32_e32 v1, v4
	v_mov_b32_e32 v3, v5
	v_pk_add_f32 v[0:1], v[0:1], v[2:3]
	v_mul_f32_e32 v2, v61, v61
	v_mul_f32_e32 v4, v63, v63
	v_mul_f32_e32 v6, v32, v32
	v_mul_f32_e32 v7, v33, v33
	v_pk_fma_f32 v[2:3], v[60:61], v[60:61], v[2:3] op_sel_hi:[1,1,0]
	v_pk_fma_f32 v[4:5], v[62:63], v[62:63], v[4:5] op_sel_hi:[1,1,0]
	v_mov_b32_e32 v3, v6
	v_mov_b32_e32 v5, v7
	v_pk_add_f32 v[2:3], v[2:3], v[4:5]
	s_waitcnt vmcnt(27)
	v_cvt_f32_f16_sdwa v159, v68 dst_sel:DWORD dst_unused:UNUSED_PAD src0_sel:WORD_1
	v_pk_add_f32 v[0:1], v[0:1], v[2:3]
	s_waitcnt vmcnt(26)
	v_cvt_f32_f16_sdwa v151, v70 dst_sel:DWORD dst_unused:UNUSED_PAD src0_sel:WORD_1
	v_add_f32_e32 v0, v0, v1
	ds_bpermute_b32 v1, v45, v0
	v_cvt_f32_f16_sdwa v105, v69 dst_sel:DWORD dst_unused:UNUSED_PAD src0_sel:WORD_1
	v_cvt_f32_f16_e32 v158, v68
	v_cvt_f32_f16_sdwa v149, v71 dst_sel:DWORD dst_unused:UNUSED_PAD src0_sel:WORD_1
	v_cvt_f32_f16_e32 v150, v70
	s_waitcnt lgkmcnt(0)
	v_add_f32_e32 v0, v0, v1
	ds_bpermute_b32 v1, v55, v0
	v_cvt_f32_f16_e32 v104, v69
	v_cvt_f32_f16_e32 v148, v71
	s_waitcnt vmcnt(25)
	v_cvt_f32_f16_e32 v136, v72
	v_cvt_f32_f16_sdwa v137, v72 dst_sel:DWORD dst_unused:UNUSED_PAD src0_sel:WORD_1
	s_waitcnt lgkmcnt(0)
	v_add_f32_e32 v0, v0, v1
	ds_bpermute_b32 v1, v65, v0
	v_cvt_f32_f16_e32 v138, v73
	v_cvt_f32_f16_sdwa v139, v73 dst_sel:DWORD dst_unused:UNUSED_PAD src0_sel:WORD_1
	v_mov_b32_e32 v2, v159
	v_mov_b32_e32 v3, v151
	s_waitcnt lgkmcnt(0)
	v_add_f32_e32 v0, v0, v1
	ds_bpermute_b32 v1, v67, v0
	v_pk_mul_f32 v[2:3], v[2:3], v[2:3]
	v_mov_b32_e32 v4, v105
	v_mov_b32_e32 v5, v149
	v_pk_mul_f32 v[4:5], v[4:5], v[4:5]
	s_waitcnt lgkmcnt(0)
	v_add_f32_e32 v0, v0, v1
	ds_bpermute_b32 v1, v172, v0
	s_waitcnt vmcnt(23)
	v_cvt_f32_f16_sdwa v93, v95 dst_sel:DWORD dst_unused:UNUSED_PAD src0_sel:WORD_1
	v_cvt_f32_f16_e32 v92, v95
	v_cvt_f32_f16_sdwa v95, v94 dst_sel:DWORD dst_unused:UNUSED_PAD src0_sel:WORD_1
	v_cvt_f32_f16_e32 v94, v94
	s_waitcnt lgkmcnt(0)
	v_add_f32_e32 v0, v0, v1
	ds_bpermute_b32 v1, v173, v0
	v_cvt_f32_f16_sdwa v121, v74 dst_sel:DWORD dst_unused:UNUSED_PAD src0_sel:WORD_1
	v_cvt_f32_f16_sdwa v123, v75 dst_sel:DWORD dst_unused:UNUSED_PAD src0_sel:WORD_1
	v_cvt_f32_f16_e32 v120, v74
	v_cvt_f32_f16_e32 v122, v75
	s_waitcnt lgkmcnt(0)
	v_add_f32_e32 v0, v0, v1
	v_fmamk_f32 v0, v0, 0x3a000000, v232
	v_rsq_f32_e32 v54, v0
	v_mov_b32_e32 v0, v158
	v_mov_b32_e32 v1, v150
	v_pk_fma_f32 v[0:1], v[0:1], v[0:1], v[2:3]
	v_mov_b32_e32 v2, v104
	v_mov_b32_e32 v3, v148
	v_pk_fma_f32 v[2:3], v[2:3], v[2:3], v[4:5]
	v_pk_mul_f32 v[4:5], v[136:137], v[136:137]
	v_pk_add_f32 v[0:1], v[0:1], v[2:3]
	v_pk_mul_f32 v[2:3], v[138:139], v[138:139]
	v_pk_add_f32 v[0:1], v[0:1], v[0:1] op_sel:[0,1] op_sel_hi:[1,0]
	v_pk_mov_b32 v[6:7], v[4:5], v[2:3] op_sel:[1,0]
	v_mov_b32_e32 v5, v3
	v_pk_add_f32 v[2:3], v[6:7], v[4:5]
	v_mul_f32_e32 v4, v94, v94
	v_mul_f32_e32 v5, v95, v95
	v_pk_add_f32 v[2:3], v[2:3], v[2:3] op_sel:[0,1] op_sel_hi:[1,0]
	v_mov_b32_e32 v1, v4
	v_mov_b32_e32 v3, v5
	s_waitcnt vmcnt(22)
	v_cvt_f32_f16_e32 v72, v96
	v_cvt_f32_f16_sdwa v73, v96 dst_sel:DWORD dst_unused:UNUSED_PAD src0_sel:WORD_1
	v_cvt_f32_f16_e32 v74, v97
	v_cvt_f32_f16_sdwa v75, v97 dst_sel:DWORD dst_unused:UNUSED_PAD src0_sel:WORD_1
	v_pk_add_f32 v[0:1], v[0:1], v[2:3]
	v_mul_f32_e32 v2, v121, v121
	v_mul_f32_e32 v4, v123, v123
	v_mul_f32_e32 v6, v92, v92
	v_mul_f32_e32 v7, v93, v93
	v_pk_fma_f32 v[2:3], v[120:121], v[120:121], v[2:3] op_sel_hi:[1,1,0]
	v_pk_fma_f32 v[4:5], v[122:123], v[122:123], v[4:5] op_sel_hi:[1,1,0]
	v_mov_b32_e32 v3, v6
	v_mov_b32_e32 v5, v7
	s_waitcnt vmcnt(20)
	v_cvt_f32_f16_sdwa v39, v106 dst_sel:DWORD dst_unused:UNUSED_PAD src0_sel:WORD_1
	v_cvt_f32_f16_e32 v38, v106
	v_pk_add_f32 v[2:3], v[2:3], v[4:5]
	v_pk_mul_f32 v[4:5], v[72:73], v[72:73]
	v_pk_add_f32 v[0:1], v[0:1], v[2:3]
	v_pk_mul_f32 v[2:3], v[74:75], v[74:75]
	v_cvt_f32_f16_sdwa v51, v98 dst_sel:DWORD dst_unused:UNUSED_PAD src0_sel:WORD_1
	v_cvt_f32_f16_sdwa v53, v99 dst_sel:DWORD dst_unused:UNUSED_PAD src0_sel:WORD_1
	v_pk_mov_b32 v[6:7], v[4:5], v[2:3] op_sel:[1,0]
	v_mov_b32_e32 v5, v3
	v_cvt_f32_f16_e32 v50, v98
	v_cvt_f32_f16_e32 v52, v99
	v_cvt_f32_f16_sdwa v37, v107 dst_sel:DWORD dst_unused:UNUSED_PAD src0_sel:WORD_1
	v_cvt_f32_f16_e32 v36, v107
	v_pk_add_f32 v[2:3], v[6:7], v[4:5]
	v_mul_f32_e32 v4, v38, v38
	v_mul_f32_e32 v5, v39, v39
	v_pk_add_f32 v[0:1], v[0:1], v[0:1] op_sel:[0,1] op_sel_hi:[1,0]
	v_pk_add_f32 v[2:3], v[2:3], v[2:3] op_sel:[0,1] op_sel_hi:[1,0]
	v_mov_b32_e32 v1, v4
	v_mov_b32_e32 v3, v5
	v_pk_add_f32 v[0:1], v[0:1], v[2:3]
	v_mul_f32_e32 v2, v51, v51
	v_mul_f32_e32 v4, v53, v53
	v_mul_f32_e32 v6, v36, v36
	v_mul_f32_e32 v7, v37, v37
	v_pk_fma_f32 v[2:3], v[50:51], v[50:51], v[2:3] op_sel_hi:[1,1,0]
	v_pk_fma_f32 v[4:5], v[52:53], v[52:53], v[4:5] op_sel_hi:[1,1,0]
	v_mov_b32_e32 v3, v6
	v_mov_b32_e32 v5, v7
	v_pk_add_f32 v[2:3], v[2:3], v[4:5]
	s_waitcnt vmcnt(19)
	v_cvt_f32_f16_sdwa v157, v128 dst_sel:DWORD dst_unused:UNUSED_PAD src0_sel:WORD_1
	v_pk_add_f32 v[0:1], v[0:1], v[2:3]
	s_waitcnt vmcnt(18)
	v_cvt_f32_f16_sdwa v155, v130 dst_sel:DWORD dst_unused:UNUSED_PAD src0_sel:WORD_1
	v_add_f32_e32 v0, v0, v1
	ds_bpermute_b32 v1, v45, v0
	v_cvt_f32_f16_sdwa v107, v129 dst_sel:DWORD dst_unused:UNUSED_PAD src0_sel:WORD_1
	v_cvt_f32_f16_e32 v156, v128
	v_cvt_f32_f16_sdwa v153, v131 dst_sel:DWORD dst_unused:UNUSED_PAD src0_sel:WORD_1
	v_cvt_f32_f16_e32 v154, v130
	s_waitcnt lgkmcnt(0)
	v_add_f32_e32 v0, v0, v1
	ds_bpermute_b32 v1, v55, v0
	v_cvt_f32_f16_e32 v106, v129
	v_cvt_f32_f16_e32 v152, v131
	s_waitcnt vmcnt(17)
	v_cvt_f32_f16_e32 v144, v146
	v_cvt_f32_f16_sdwa v145, v146 dst_sel:DWORD dst_unused:UNUSED_PAD src0_sel:WORD_1
	s_waitcnt lgkmcnt(0)
	v_add_f32_e32 v0, v0, v1
	ds_bpermute_b32 v1, v65, v0
	v_cvt_f32_f16_e32 v146, v147
	v_cvt_f32_f16_sdwa v147, v147 dst_sel:DWORD dst_unused:UNUSED_PAD src0_sel:WORD_1
	v_mov_b32_e32 v2, v157
	v_mov_b32_e32 v3, v155
	s_waitcnt lgkmcnt(0)
	v_add_f32_e32 v0, v0, v1
	ds_bpermute_b32 v1, v67, v0
	v_pk_mul_f32 v[2:3], v[2:3], v[2:3]
	v_mov_b32_e32 v4, v107
	v_mov_b32_e32 v5, v153
	v_pk_mul_f32 v[4:5], v[4:5], v[4:5]
	s_waitcnt lgkmcnt(0)
	v_add_f32_e32 v0, v0, v1
	ds_bpermute_b32 v1, v172, v0
	s_waitcnt vmcnt(15)
	v_cvt_f32_f16_sdwa v99, v166 dst_sel:DWORD dst_unused:UNUSED_PAD src0_sel:WORD_1
	v_cvt_f32_f16_e32 v98, v166
	v_cvt_f32_f16_sdwa v129, v164 dst_sel:DWORD dst_unused:UNUSED_PAD src0_sel:WORD_1
	v_cvt_f32_f16_sdwa v131, v165 dst_sel:DWORD dst_unused:UNUSED_PAD src0_sel:WORD_1
	s_waitcnt lgkmcnt(0)
	v_add_f32_e32 v0, v0, v1
	ds_bpermute_b32 v1, v173, v0
	v_cvt_f32_f16_e32 v128, v164
	v_cvt_f32_f16_e32 v130, v165
	v_cvt_f32_f16_sdwa v97, v167 dst_sel:DWORD dst_unused:UNUSED_PAD src0_sel:WORD_1
	v_cvt_f32_f16_e32 v96, v167
	s_waitcnt lgkmcnt(0)
	v_add_f32_e32 v0, v0, v1
	v_fmamk_f32 v0, v0, 0x3a000000, v232
	v_rsq_f32_e32 v64, v0
	v_mov_b32_e32 v0, v156
	v_mov_b32_e32 v1, v154
	v_pk_fma_f32 v[0:1], v[0:1], v[0:1], v[2:3]
	v_mov_b32_e32 v2, v106
	v_mov_b32_e32 v3, v152
	v_pk_fma_f32 v[2:3], v[2:3], v[2:3], v[4:5]
	v_pk_mul_f32 v[4:5], v[144:145], v[144:145]
	v_pk_add_f32 v[0:1], v[0:1], v[2:3]
	v_pk_mul_f32 v[2:3], v[146:147], v[146:147]
	v_pk_add_f32 v[0:1], v[0:1], v[0:1] op_sel:[0,1] op_sel_hi:[1,0]
	v_pk_mov_b32 v[6:7], v[4:5], v[2:3] op_sel:[1,0]
	v_mov_b32_e32 v5, v3
	v_pk_add_f32 v[2:3], v[6:7], v[4:5]
	v_mul_f32_e32 v4, v98, v98
	v_mul_f32_e32 v5, v99, v99
	v_pk_add_f32 v[2:3], v[2:3], v[2:3] op_sel:[0,1] op_sel_hi:[1,0]
	v_mov_b32_e32 v1, v4
	v_mov_b32_e32 v3, v5
	s_waitcnt vmcnt(14)
	v_cvt_f32_f16_e32 v68, v168
	v_cvt_f32_f16_sdwa v69, v168 dst_sel:DWORD dst_unused:UNUSED_PAD src0_sel:WORD_1
	v_cvt_f32_f16_e32 v70, v169
	v_cvt_f32_f16_sdwa v71, v169 dst_sel:DWORD dst_unused:UNUSED_PAD src0_sel:WORD_1
	v_pk_add_f32 v[0:1], v[0:1], v[2:3]
	v_mul_f32_e32 v2, v129, v129
	v_mul_f32_e32 v4, v131, v131
	v_mul_f32_e32 v6, v96, v96
	v_mul_f32_e32 v7, v97, v97
	v_pk_fma_f32 v[2:3], v[128:129], v[128:129], v[2:3] op_sel_hi:[1,1,0]
	v_pk_fma_f32 v[4:5], v[130:131], v[130:131], v[4:5] op_sel_hi:[1,1,0]
	v_mov_b32_e32 v3, v6
	v_mov_b32_e32 v5, v7
	s_waitcnt vmcnt(12)
	v_cvt_f32_f16_sdwa v43, v176 dst_sel:DWORD dst_unused:UNUSED_PAD src0_sel:WORD_1
	v_cvt_f32_f16_e32 v42, v176
	v_pk_add_f32 v[2:3], v[2:3], v[4:5]
	v_pk_mul_f32 v[4:5], v[68:69], v[68:69]
	v_pk_add_f32 v[0:1], v[0:1], v[2:3]
	v_pk_mul_f32 v[2:3], v[70:71], v[70:71]
	v_cvt_f32_f16_sdwa v47, v170 dst_sel:DWORD dst_unused:UNUSED_PAD src0_sel:WORD_1
	v_cvt_f32_f16_sdwa v49, v171 dst_sel:DWORD dst_unused:UNUSED_PAD src0_sel:WORD_1
	v_pk_mov_b32 v[6:7], v[4:5], v[2:3] op_sel:[1,0]
	v_mov_b32_e32 v5, v3
	v_cvt_f32_f16_e32 v46, v170
	v_cvt_f32_f16_e32 v48, v171
	v_cvt_f32_f16_sdwa v41, v177 dst_sel:DWORD dst_unused:UNUSED_PAD src0_sel:WORD_1
	v_cvt_f32_f16_e32 v40, v177
	v_pk_add_f32 v[2:3], v[6:7], v[4:5]
	v_mul_f32_e32 v4, v42, v42
	v_mul_f32_e32 v5, v43, v43
	v_pk_add_f32 v[0:1], v[0:1], v[0:1] op_sel:[0,1] op_sel_hi:[1,0]
	v_pk_add_f32 v[2:3], v[2:3], v[2:3] op_sel:[0,1] op_sel_hi:[1,0]
	v_mov_b32_e32 v1, v4
	v_mov_b32_e32 v3, v5
	v_pk_add_f32 v[0:1], v[0:1], v[2:3]
	v_mul_f32_e32 v2, v47, v47
	v_mul_f32_e32 v4, v49, v49
	v_mul_f32_e32 v6, v40, v40
	v_mul_f32_e32 v7, v41, v41
	v_pk_fma_f32 v[2:3], v[46:47], v[46:47], v[2:3] op_sel_hi:[1,1,0]
	v_pk_fma_f32 v[4:5], v[48:49], v[48:49], v[4:5] op_sel_hi:[1,1,0]
	v_mov_b32_e32 v3, v6
	v_mov_b32_e32 v5, v7
	v_pk_add_f32 v[2:3], v[2:3], v[4:5]
	v_mad_i64_i32 v[166:167], s[52:53], s5, v237, v[22:23]
	v_pk_add_f32 v[0:1], v[0:1], v[2:3]
	v_mad_i64_i32 v[164:165], s[52:53], s5, v237, v[24:25]
	v_add_f32_e32 v0, v0, v1
	ds_bpermute_b32 v1, v45, v0
	v_pk_mul_f32 v[100:101], v[44:45], v[100:101] op_sel_hi:[0,1]
	v_pk_mul_f32 v[162:163], v[44:45], v[162:163] op_sel_hi:[0,1]
	v_pk_mul_f32 v[102:103], v[54:55], v[102:103] op_sel_hi:[0,1]
	v_pk_mul_f32 v[160:161], v[54:55], v[160:161] op_sel_hi:[0,1]
	s_waitcnt lgkmcnt(0)
	v_add_f32_e32 v0, v0, v1
	ds_bpermute_b32 v1, v55, v0
	v_pk_mul_f32 v[104:105], v[64:65], v[104:105] op_sel_hi:[0,1]
	v_pk_mul_f32 v[158:159], v[64:65], v[158:159] op_sel_hi:[0,1]
	v_pk_mul_f32 v[132:133], v[44:45], v[132:133] op_sel_hi:[0,1]
	v_pk_mul_f32 v[134:135], v[44:45], v[134:135] op_sel_hi:[0,1]
	s_waitcnt lgkmcnt(0)
	v_add_f32_e32 v0, v0, v1
	ds_bpermute_b32 v1, v65, v0
	v_pk_mul_f32 v[118:119], v[44:45], v[118:119] op_sel_hi:[0,1]
	v_pk_mul_f32 v[116:117], v[44:45], v[116:117] op_sel_hi:[0,1]
	v_pk_mul_f32 v[110:111], v[44:45], v[110:111] op_sel_hi:[0,1]
	v_pk_mul_f32 v[108:109], v[44:45], v[108:109] op_sel_hi:[0,1]
	s_waitcnt lgkmcnt(0)
	v_add_f32_e32 v0, v0, v1
	ds_bpermute_b32 v1, v67, v0
	v_pk_mul_f32 v[86:87], v[44:45], v[86:87] op_sel_hi:[0,1]
	v_pk_mul_f32 v[84:85], v[44:45], v[84:85] op_sel_hi:[0,1]
	v_pk_mul_f32 v[82:83], v[44:45], v[82:83] op_sel_hi:[0,1]
	v_pk_mul_f32 v[80:81], v[44:45], v[80:81] op_sel_hi:[0,1]
	s_waitcnt lgkmcnt(0)
	v_add_f32_e32 v0, v0, v1
	ds_bpermute_b32 v1, v172, v0
	v_pk_mul_f32 v[78:79], v[54:55], v[78:79] op_sel_hi:[0,1]
	v_pk_mul_f32 v[76:77], v[54:55], v[76:77] op_sel_hi:[0,1]
	v_pk_mul_f32 v[74:75], v[64:65], v[74:75] op_sel_hi:[0,1]
	v_pk_mul_f32 v[72:73], v[64:65], v[72:73] op_sel_hi:[0,1]
	s_waitcnt lgkmcnt(0)
	v_add_f32_e32 v0, v0, v1
	ds_bpermute_b32 v1, v173, v0
	v_pk_mul_f32 v[58:59], v[44:45], v[58:59] op_sel_hi:[0,1]
	v_pk_mul_f32 v[56:57], v[44:45], v[56:57] op_sel_hi:[0,1]
	v_pk_mul_f32 v[52:53], v[64:65], v[52:53] op_sel_hi:[0,1]
	v_pk_mul_f32 v[50:51], v[64:65], v[50:51] op_sel_hi:[0,1]
	s_waitcnt lgkmcnt(0)
	v_add_f32_e32 v0, v0, v1
	v_fmamk_f32 v0, v0, 0x3a000000, v232
	v_rsq_f32_e32 v66, v0
	v_pk_mul_f32 v[28:29], v[44:45], v[28:29] op_sel_hi:[0,1]
	v_pk_mul_f32 v[30:31], v[44:45], v[30:31] op_sel_hi:[0,1]
	v_pk_mul_f32 v[106:107], v[66:67], v[106:107] op_sel_hi:[0,1]
	v_pk_mul_f32 v[156:157], v[66:67], v[156:157] op_sel_hi:[0,1]
	v_pk_mul_f32 v[70:71], v[66:67], v[70:71] op_sel_hi:[0,1]
	v_pk_mul_f32 v[68:69], v[66:67], v[68:69] op_sel_hi:[0,1]
	v_pk_mul_f32 v[48:49], v[66:67], v[48:49] op_sel_hi:[0,1]
	v_pk_mul_f32 v[46:47], v[66:67], v[46:47] op_sel_hi:[0,1]
	s_waitcnt vmcnt(9)
	v_pk_mul_f32 v[162:163], v[162:163], v[180:181]
	v_pk_mul_f32 v[100:101], v[100:101], v[182:183]
	v_pk_add_f32 v[168:169], v[190:191], 1.0 op_sel_hi:[1,0]
	v_pk_add_f32 v[170:171], v[188:189], 1.0 op_sel_hi:[1,0]
	v_pk_fma_f32 v[100:101], v[100:101], v[168:169], v[186:187]
	v_pk_fma_f32 v[162:163], v[162:163], v[170:171], v[184:185]
	v_pk_mul_f32 v[160:161], v[160:161], v[180:181]
	v_cvt_pk_bf16_f32 v162, v162, v163
	v_cvt_pk_bf16_f32 v163, v100, v101
	v_lshl_add_u64 v[100:101], s[14:15], 0, v[18:19]
	v_pk_mul_f32 v[102:103], v[102:103], v[182:183]
	v_add_co_u32_e32 v100, vcc, s30, v100
	v_pk_fma_f32 v[102:103], v[102:103], v[168:169], v[186:187]
	v_pk_fma_f32 v[160:161], v[160:161], v[170:171], v[184:185]
	v_addc_co_u32_e32 v101, vcc, 0, v101, vcc
	v_cvt_pk_bf16_f32 v160, v160, v161
	v_cvt_pk_bf16_f32 v161, v102, v103
	v_lshl_add_u64 v[102:103], s[8:9], 0, v[18:19]
	v_pk_mul_f32 v[158:159], v[180:181], v[158:159]
	v_pk_mul_f32 v[104:105], v[182:183], v[104:105]
	v_pk_mul_f32 v[180:181], v[180:181], v[156:157]
	v_pk_mul_f32 v[182:183], v[182:183], v[106:107]
	v_add_co_u32_e32 v102, vcc, s30, v102
	v_pk_fma_f32 v[104:105], v[104:105], v[168:169], v[186:187]
	v_pk_fma_f32 v[158:159], v[158:159], v[170:171], v[184:185]
	v_pk_fma_f32 v[186:187], v[168:169], v[182:183], v[186:187]
	v_pk_fma_f32 v[184:185], v[170:171], v[180:181], v[184:185]
	v_addc_co_u32_e32 v103, vcc, 0, v103, vcc
	v_cvt_pk_bf16_f32 v158, v158, v159
	v_cvt_pk_bf16_f32 v159, v104, v105
	v_lshl_add_u64 v[104:105], v[26:27], 0, s[18:19]
	v_cvt_pk_bf16_f32 v184, v184, v185
	v_cvt_pk_bf16_f32 v185, v186, v187
	v_lshl_add_u64 v[106:107], v[26:27], 0, s[22:23]
	global_store_dwordx2 v[100:101], v[162:163], off
	global_store_dwordx2 v[102:103], v[160:161], off
	global_store_dwordx2 v[104:105], v[158:159], off
	global_store_dwordx2 v[106:107], v[184:185], off
	global_load_dwordx4 v[180:183], v[10:11], off
	global_load_dwordx4 v[184:187], v[252:253], off
	global_load_dwordx4 v[188:191], v[250:251], off
	s_nop 0
	s_cselect_b64 s[18:19], -1, 0
	s_add_u32 s8, s8, s10
	s_addc_u32 s9, s9, s11
	s_add_u32 s12, s12, s10
	s_addc_u32 s13, s13, s11
	s_add_u32 s14, s14, s10
	s_addc_u32 s15, s15, s11
	s_add_u32 s16, s16, s10
	s_addc_u32 s17, s17, s11
	s_waitcnt vmcnt(13)
	v_pk_mul_f32 v[134:135], v[134:135], v[196:197]
	v_pk_mul_f32 v[132:133], v[132:133], v[198:199]
	v_pk_add_f32 v[206:207], v[206:207], 1.0 op_sel_hi:[1,0]
	v_pk_add_f32 v[204:205], v[204:205], 1.0 op_sel_hi:[1,0]
	v_pk_fma_f32 v[132:133], v[132:133], v[206:207], v[202:203]
	v_pk_fma_f32 v[134:135], v[134:135], v[204:205], v[200:201]
	s_nop 0
	v_cvt_pk_bf16_f32 v134, v134, v135
	v_cvt_pk_bf16_f32 v135, v132, v133
	global_store_dwordx2 v[100:101], v[134:135], off offset:512
	v_pk_mul_f32 v[132:133], v[54:55], v[140:141] op_sel_hi:[0,1]
	v_pk_mul_f32 v[134:135], v[54:55], v[142:143] op_sel_hi:[0,1]
	v_pk_mul_f32 v[134:135], v[134:135], v[196:197]
	v_pk_mul_f32 v[132:133], v[132:133], v[198:199]
	v_pk_fma_f32 v[134:135], v[134:135], v[204:205], v[200:201]
	v_pk_fma_f32 v[132:133], v[132:133], v[206:207], v[202:203]
	v_cvt_pk_bf16_f32 v134, v134, v135
	v_cvt_pk_bf16_f32 v135, v132, v133
	global_store_dwordx2 v[102:103], v[134:135], off offset:512
	v_pk_mul_f32 v[132:133], v[64:65], v[148:149] op_sel_hi:[0,1]
	v_pk_mul_f32 v[134:135], v[64:65], v[150:151] op_sel_hi:[0,1]
	v_pk_mul_f32 v[134:135], v[134:135], v[196:197]
	v_pk_mul_f32 v[132:133], v[132:133], v[198:199]
	v_pk_fma_f32 v[134:135], v[134:135], v[204:205], v[200:201]
	v_pk_fma_f32 v[132:133], v[132:133], v[206:207], v[202:203]
	v_cvt_pk_bf16_f32 v134, v134, v135
	v_cvt_pk_bf16_f32 v135, v132, v133
	global_store_dwordx2 v[104:105], v[134:135], off offset:512
	v_pk_mul_f32 v[132:133], v[66:67], v[152:153] op_sel_hi:[0,1]
	v_pk_mul_f32 v[134:135], v[66:67], v[154:155] op_sel_hi:[0,1]
	v_pk_mul_f32 v[196:197], v[196:197], v[134:135]
	v_pk_mul_f32 v[198:199], v[198:199], v[132:133]
	v_pk_fma_f32 v[196:197], v[196:197], v[204:205], v[200:201]
	v_pk_fma_f32 v[198:199], v[198:199], v[206:207], v[202:203]
	v_cvt_pk_bf16_f32 v196, v196, v197
	v_cvt_pk_bf16_f32 v197, v198, v199
	global_store_dwordx2 v[106:107], v[196:197], off offset:512
	global_load_dwordx4 v[196:199], v[12:13], off
	global_load_dwordx4 v[200:203], v[250:251], off offset:1024
	global_load_dwordx4 v[204:207], v[252:253], off offset:1024
	s_nop 0
	s_waitcnt vmcnt(17)
	v_pk_mul_f32 v[116:117], v[116:117], v[208:209]
	v_pk_mul_f32 v[118:119], v[118:119], v[210:211]
	v_pk_add_f32 v[220:221], v[220:221], 1.0 op_sel_hi:[1,0]
	v_pk_add_f32 v[218:219], v[218:219], 1.0 op_sel_hi:[1,0]
	v_pk_fma_f32 v[118:119], v[118:119], v[220:221], v[214:215]
	v_pk_fma_f32 v[116:117], v[116:117], v[218:219], v[212:213]
	s_nop 0
	v_cvt_pk_bf16_f32 v116, v116, v117
	v_cvt_pk_bf16_f32 v117, v118, v119
	global_store_dwordx2 v[100:101], v[116:117], off offset:1024
	v_pk_mul_f32 v[116:117], v[54:55], v[126:127] op_sel_hi:[0,1]
	v_pk_mul_f32 v[118:119], v[54:55], v[124:125] op_sel_hi:[0,1]
	v_pk_mul_f32 v[118:119], v[118:119], v[208:209]
	v_pk_mul_f32 v[116:117], v[116:117], v[210:211]
	v_pk_fma_f32 v[118:119], v[118:119], v[218:219], v[212:213]
	v_pk_fma_f32 v[116:117], v[116:117], v[220:221], v[214:215]
	v_cvt_pk_bf16_f32 v118, v118, v119
	v_cvt_pk_bf16_f32 v119, v116, v117
	global_store_dwordx2 v[102:103], v[118:119], off offset:1024
	v_pk_mul_f32 v[116:117], v[64:65], v[138:139] op_sel_hi:[0,1]
	v_pk_mul_f32 v[118:119], v[64:65], v[136:137] op_sel_hi:[0,1]
	v_pk_mul_f32 v[118:119], v[118:119], v[208:209]
	v_pk_mul_f32 v[116:117], v[116:117], v[210:211]
	v_pk_fma_f32 v[118:119], v[118:119], v[218:219], v[212:213]
	v_pk_fma_f32 v[116:117], v[116:117], v[220:221], v[214:215]
	v_cvt_pk_bf16_f32 v118, v118, v119
	v_cvt_pk_bf16_f32 v119, v116, v117
	global_store_dwordx2 v[104:105], v[118:119], off offset:1024
	v_pk_mul_f32 v[116:117], v[66:67], v[146:147] op_sel_hi:[0,1]
	v_pk_mul_f32 v[118:119], v[66:67], v[144:145] op_sel_hi:[0,1]
	v_pk_mul_f32 v[208:209], v[118:119], v[208:209]
	v_pk_mul_f32 v[210:211], v[116:117], v[210:211]
	v_pk_fma_f32 v[208:209], v[208:209], v[218:219], v[212:213]
	v_pk_fma_f32 v[210:211], v[210:211], v[220:221], v[214:215]
	v_cvt_pk_bf16_f32 v208, v208, v209
	v_cvt_pk_bf16_f32 v209, v210, v211
	global_store_dwordx2 v[106:107], v[208:209], off offset:1024
	global_load_dwordx4 v[208:211], v[14:15], off
	global_load_dwordx4 v[212:215], v[250:251], off offset:2048
	global_load_dwordx4 v[218:221], v[252:253], off offset:2048
	s_nop 0
	s_waitcnt vmcnt(21)
	v_pk_mul_f32 v[108:109], v[108:109], v[222:223]
	v_pk_mul_f32 v[110:111], v[110:111], v[224:225]
	v_pk_add_f32 v[244:245], v[244:245], 1.0 op_sel_hi:[1,0]
	v_pk_add_f32 v[242:243], v[242:243], 1.0 op_sel_hi:[1,0]
	v_pk_fma_f32 v[110:111], v[110:111], v[244:245], v[228:229]
	v_pk_fma_f32 v[108:109], v[108:109], v[242:243], v[226:227]
	s_nop 0
	v_cvt_pk_bf16_f32 v108, v108, v109
	v_cvt_pk_bf16_f32 v109, v110, v111
	global_store_dwordx2 v[100:101], v[108:109], off offset:1536
	v_pk_mul_f32 v[108:109], v[54:55], v[114:115] op_sel_hi:[0,1]
	v_pk_mul_f32 v[110:111], v[54:55], v[112:113] op_sel_hi:[0,1]
	v_pk_mul_f32 v[110:111], v[110:111], v[222:223]
	v_pk_mul_f32 v[108:109], v[108:109], v[224:225]
	v_pk_fma_f32 v[110:111], v[110:111], v[242:243], v[226:227]
	v_pk_fma_f32 v[108:109], v[108:109], v[244:245], v[228:229]
	v_cvt_pk_bf16_f32 v110, v110, v111
	v_cvt_pk_bf16_f32 v111, v108, v109
	global_store_dwordx2 v[102:103], v[110:111], off offset:1536
	v_pk_mul_f32 v[108:109], v[64:65], v[122:123] op_sel_hi:[0,1]
	v_pk_mul_f32 v[110:111], v[64:65], v[120:121] op_sel_hi:[0,1]
	v_pk_mul_f32 v[110:111], v[110:111], v[222:223]
	v_pk_mul_f32 v[108:109], v[108:109], v[224:225]
	v_pk_fma_f32 v[110:111], v[110:111], v[242:243], v[226:227]
	v_pk_fma_f32 v[108:109], v[108:109], v[244:245], v[228:229]
	v_cvt_pk_bf16_f32 v110, v110, v111
	v_cvt_pk_bf16_f32 v111, v108, v109
	global_store_dwordx2 v[104:105], v[110:111], off offset:1536
	v_pk_mul_f32 v[108:109], v[66:67], v[130:131] op_sel_hi:[0,1]
	v_pk_mul_f32 v[110:111], v[66:67], v[128:129] op_sel_hi:[0,1]
	v_pk_mul_f32 v[222:223], v[110:111], v[222:223]
	v_pk_mul_f32 v[224:225], v[108:109], v[224:225]
	v_add_co_u32_e32 v108, vcc, s77, v166
	v_pk_fma_f32 v[224:225], v[224:225], v[244:245], v[228:229]
	v_pk_fma_f32 v[222:223], v[222:223], v[242:243], v[226:227]
	v_addc_co_u32_e32 v109, vcc, 0, v167, vcc
	v_cvt_pk_bf16_f32 v222, v222, v223
	v_cvt_pk_bf16_f32 v223, v224, v225
	v_add_co_u32_e32 v110, vcc, s77, v164
	global_store_dwordx2 v[106:107], v[222:223], off offset:1536
	global_load_dwordx4 v[222:225], v[16:17], off
	global_load_dwordx4 v[226:229], v[250:251], off offset:3072
	global_load_dwordx4 v[242:245], v[252:253], off offset:3072
	s_nop 0
	v_addc_co_u32_e32 v111, vcc, 0, v165, vcc
	v_subrev_co_u32_e32 v174, vcc, 1, v174
	s_waitcnt vmcnt(21)
	v_pk_mul_f32 v[84:85], v[84:85], v[180:181]
	v_pk_add_f32 v[112:113], v[186:187], 1.0 op_sel_hi:[1,0]
	v_pk_add_f32 v[184:185], v[184:185], 1.0 op_sel_hi:[1,0]
	v_pk_mul_f32 v[86:87], v[86:87], v[182:183]
	v_pk_fma_f32 v[84:85], v[84:85], v[184:185], v[188:189]
	v_pk_fma_f32 v[86:87], v[86:87], v[112:113], v[190:191]
	v_cvt_pk_bf16_f32 v84, v84, v85
	v_cvt_pk_bf16_f32 v85, v86, v87
	global_store_dwordx2 v[100:101], v[84:85], off offset:2048
	v_pk_mul_f32 v[84:85], v[54:55], v[88:89] op_sel_hi:[0,1]
	v_pk_mul_f32 v[86:87], v[54:55], v[90:91] op_sel_hi:[0,1]
	v_pk_mul_f32 v[86:87], v[86:87], v[180:181]
	v_pk_mul_f32 v[84:85], v[84:85], v[182:183]
	v_pk_fma_f32 v[86:87], v[86:87], v[184:185], v[188:189]
	v_pk_fma_f32 v[84:85], v[84:85], v[112:113], v[190:191]
	v_cvt_pk_bf16_f32 v86, v86, v87
	v_cvt_pk_bf16_f32 v87, v84, v85
	global_store_dwordx2 v[102:103], v[86:87], off offset:2048
	v_pk_mul_f32 v[84:85], v[64:65], v[92:93] op_sel_hi:[0,1]
	v_pk_mul_f32 v[86:87], v[64:65], v[94:95] op_sel_hi:[0,1]
	v_pk_mul_f32 v[86:87], v[86:87], v[180:181]
	v_pk_mul_f32 v[84:85], v[84:85], v[182:183]
	v_pk_fma_f32 v[86:87], v[86:87], v[184:185], v[188:189]
	v_pk_fma_f32 v[84:85], v[84:85], v[112:113], v[190:191]
	v_cvt_pk_bf16_f32 v86, v86, v87
	v_cvt_pk_bf16_f32 v87, v84, v85
	global_store_dwordx2 v[104:105], v[86:87], off offset:2048
	v_pk_mul_f32 v[84:85], v[66:67], v[96:97] op_sel_hi:[0,1]
	v_pk_mul_f32 v[86:87], v[66:67], v[98:99] op_sel_hi:[0,1]
	v_pk_mul_f32 v[180:181], v[86:87], v[180:181]
	v_pk_mul_f32 v[182:183], v[84:85], v[182:183]
	v_pk_fma_f32 v[180:181], v[180:181], v[184:185], v[188:189]
	v_pk_fma_f32 v[182:183], v[182:183], v[112:113], v[190:191]
	v_cvt_pk_bf16_f32 v180, v180, v181
	v_cvt_pk_bf16_f32 v181, v182, v183
	global_store_dwordx2 v[106:107], v[180:181], off offset:2048
	s_nop 0
	s_waitcnt vmcnt(18)
	v_pk_mul_f32 v[80:81], v[80:81], v[196:197]
	v_pk_mul_f32 v[82:83], v[82:83], v[198:199]
	v_pk_add_f32 v[84:85], v[206:207], 1.0 op_sel_hi:[1,0]
	v_pk_add_f32 v[204:205], v[204:205], 1.0 op_sel_hi:[1,0]
	v_pk_mul_f32 v[76:77], v[76:77], v[196:197]
	v_pk_mul_f32 v[78:79], v[78:79], v[198:199]
	v_pk_mul_f32 v[72:73], v[72:73], v[196:197]
	v_pk_mul_f32 v[74:75], v[74:75], v[198:199]
	v_pk_mul_f32 v[196:197], v[68:69], v[196:197]
	v_pk_mul_f32 v[198:199], v[70:71], v[198:199]
	v_pk_fma_f32 v[82:83], v[82:83], v[84:85], v[202:203]
	v_pk_fma_f32 v[80:81], v[80:81], v[204:205], v[200:201]
	v_pk_fma_f32 v[78:79], v[78:79], v[84:85], v[202:203]
	v_pk_fma_f32 v[76:77], v[76:77], v[204:205], v[200:201]
	v_pk_fma_f32 v[74:75], v[74:75], v[84:85], v[202:203]
	v_pk_fma_f32 v[72:73], v[72:73], v[204:205], v[200:201]
	v_pk_fma_f32 v[202:203], v[198:199], v[84:85], v[202:203]
	v_pk_fma_f32 v[200:201], v[196:197], v[204:205], v[200:201]
	v_cvt_pk_bf16_f32 v80, v80, v81
	v_cvt_pk_bf16_f32 v81, v82, v83
	v_cvt_pk_bf16_f32 v76, v76, v77
	v_cvt_pk_bf16_f32 v77, v78, v79
	v_cvt_pk_bf16_f32 v72, v72, v73
	v_cvt_pk_bf16_f32 v73, v74, v75
	v_cvt_pk_bf16_f32 v200, v200, v201
	v_cvt_pk_bf16_f32 v201, v202, v203
	global_store_dwordx2 v[100:101], v[80:81], off offset:2560
	global_store_dwordx2 v[102:103], v[76:77], off offset:2560
	global_store_dwordx2 v[104:105], v[72:73], off offset:2560
	global_store_dwordx2 v[106:107], v[200:201], off offset:2560
	s_nop 0
	s_waitcnt vmcnt(15)
	v_pk_mul_f32 v[56:57], v[56:57], v[208:209]
	v_pk_mul_f32 v[58:59], v[58:59], v[210:211]
	v_pk_add_f32 v[220:221], v[220:221], 1.0 op_sel_hi:[1,0]
	v_pk_add_f32 v[218:219], v[218:219], 1.0 op_sel_hi:[1,0]
	v_pk_fma_f32 v[58:59], v[58:59], v[220:221], v[214:215]
	v_pk_fma_f32 v[56:57], v[56:57], v[218:219], v[212:213]
	v_pk_mul_f32 v[50:51], v[50:51], v[208:209]
	v_cvt_pk_bf16_f32 v56, v56, v57
	v_cvt_pk_bf16_f32 v57, v58, v59
	global_store_dwordx2 v[100:101], v[56:57], off offset:3072
	v_pk_mul_f32 v[56:57], v[54:55], v[62:63] op_sel_hi:[0,1]
	v_pk_mul_f32 v[58:59], v[54:55], v[60:61] op_sel_hi:[0,1]
	v_pk_mul_f32 v[58:59], v[58:59], v[208:209]
	v_pk_mul_f32 v[56:57], v[56:57], v[210:211]
	v_pk_mul_f32 v[52:53], v[52:53], v[210:211]
	v_pk_mul_f32 v[208:209], v[46:47], v[208:209]
	v_pk_mul_f32 v[210:211], v[48:49], v[210:211]
	v_pk_fma_f32 v[56:57], v[56:57], v[220:221], v[214:215]
	v_pk_fma_f32 v[58:59], v[58:59], v[218:219], v[212:213]
	v_pk_fma_f32 v[52:53], v[52:53], v[220:221], v[214:215]
	v_pk_fma_f32 v[50:51], v[50:51], v[218:219], v[212:213]
	v_pk_fma_f32 v[210:211], v[210:211], v[220:221], v[214:215]
	v_pk_fma_f32 v[208:209], v[208:209], v[218:219], v[212:213]
	v_cvt_pk_bf16_f32 v58, v58, v59
	v_cvt_pk_bf16_f32 v59, v56, v57
	v_cvt_pk_bf16_f32 v50, v50, v51
	v_cvt_pk_bf16_f32 v51, v52, v53
	v_cvt_pk_bf16_f32 v208, v208, v209
	v_cvt_pk_bf16_f32 v209, v210, v211
	global_store_dwordx2 v[102:103], v[58:59], off offset:3072
	global_store_dwordx2 v[104:105], v[50:51], off offset:3072
	global_store_dwordx2 v[106:107], v[208:209], off offset:3072
	s_nop 0
	s_waitcnt vmcnt(12)
	v_pk_mul_f32 v[30:31], v[30:31], v[222:223]
	v_pk_mul_f32 v[28:29], v[28:29], v[224:225]
	v_pk_add_f32 v[244:245], v[244:245], 1.0 op_sel_hi:[1,0]
	v_pk_add_f32 v[242:243], v[242:243], 1.0 op_sel_hi:[1,0]
	v_pk_fma_f32 v[28:29], v[28:29], v[244:245], v[228:229]
	v_pk_fma_f32 v[30:31], v[30:31], v[242:243], v[226:227]
	s_nop 0
	v_cvt_pk_bf16_f32 v30, v30, v31
	v_cvt_pk_bf16_f32 v31, v28, v29
	global_store_dwordx2 v[100:101], v[30:31], off offset:3584
	v_pk_mul_f32 v[28:29], v[54:55], v[32:33] op_sel_hi:[0,1]
	v_pk_mul_f32 v[30:31], v[54:55], v[34:35] op_sel_hi:[0,1]
	v_pk_mul_f32 v[30:31], v[30:31], v[222:223]
	v_pk_mul_f32 v[28:29], v[28:29], v[224:225]
	v_pk_fma_f32 v[30:31], v[30:31], v[242:243], v[226:227]
	v_pk_fma_f32 v[28:29], v[28:29], v[244:245], v[228:229]
	v_cvt_pk_bf16_f32 v30, v30, v31
	v_cvt_pk_bf16_f32 v31, v28, v29
	global_store_dwordx2 v[102:103], v[30:31], off offset:3584
	v_pk_mul_f32 v[28:29], v[64:65], v[36:37] op_sel_hi:[0,1]
	v_pk_mul_f32 v[30:31], v[64:65], v[38:39] op_sel_hi:[0,1]
	v_pk_mul_f32 v[30:31], v[30:31], v[222:223]
	v_pk_mul_f32 v[28:29], v[28:29], v[224:225]
	v_pk_fma_f32 v[30:31], v[30:31], v[242:243], v[226:227]
	v_pk_fma_f32 v[28:29], v[28:29], v[244:245], v[228:229]
	v_cvt_pk_bf16_f32 v30, v30, v31
	v_cvt_pk_bf16_f32 v31, v28, v29
	global_store_dwordx2 v[104:105], v[30:31], off offset:3584
	v_pk_mul_f32 v[28:29], v[66:67], v[40:41] op_sel_hi:[0,1]
	v_pk_mul_f32 v[30:31], v[66:67], v[42:43] op_sel_hi:[0,1]
	v_pk_mul_f32 v[222:223], v[30:31], v[222:223]
	v_pk_mul_f32 v[224:225], v[28:29], v[224:225]
	v_pk_fma_f32 v[222:223], v[222:223], v[242:243], v[226:227]
	v_pk_fma_f32 v[224:225], v[224:225], v[244:245], v[228:229]
	v_cvt_pk_bf16_f32 v222, v222, v223
	v_cvt_pk_bf16_f32 v223, v224, v225
	global_store_dwordx2 v[106:107], v[222:223], off offset:3584
	v_cndmask_b32_e64 v0, 0, 1, vcc
	v_cndmask_b32_e64 v1, 0, 1, s[18:19]
	v_cndmask_b32_e64 v0, v1, v0, s[2:3]
	v_and_b32_e32 v0, 1, v0
	v_cmp_eq_u32_e32 vcc, 1, v0
	s_cbranch_vccnz .LBB0_262

.LBB0_689:
	v_lshl_add_u64 v[0:1], s[16:17], 0, v[18:19]
	v_add_co_u32_e32 v0, vcc, 0x3000000, v0
	v_lshl_add_u64 v[36:37], s[12:13], 0, v[18:19]
	s_nop 0
	v_addc_co_u32_e32 v1, vcc, 0, v1, vcc
	global_load_dwordx2 v[2:3], v[0:1], off
	global_load_dwordx2 v[4:5], v[0:1], off offset:512
	global_load_dwordx2 v[6:7], v[0:1], off offset:1024
	global_load_dwordx2 v[28:29], v[0:1], off offset:1536
	global_load_dwordx2 v[30:31], v[0:1], off offset:2048
	global_load_dwordx2 v[32:33], v[0:1], off offset:2560
	global_load_dwordx2 v[34:35], v[0:1], off offset:3072
	s_nop 0
	global_load_dwordx2 v[0:1], v[0:1], off offset:3584
	v_add_co_u32_e32 v36, vcc, 0x3000000, v36
	s_add_i32 s18, s4, 2
	s_nop 0
	v_addc_co_u32_e32 v37, vcc, 0, v37, vcc
	global_load_dwordx2 v[38:39], v[36:37], off
	global_load_dwordx2 v[40:41], v[36:37], off offset:512
	global_load_dwordx2 v[42:43], v[36:37], off offset:1024
	global_load_dwordx2 v[46:47], v[36:37], off offset:1536
	global_load_dwordx2 v[48:49], v[36:37], off offset:2048
	global_load_dwordx2 v[50:51], v[36:37], off offset:2560
	global_load_dwordx2 v[52:53], v[36:37], off offset:3072
	s_nop 0
	global_load_dwordx2 v[36:37], v[36:37], off offset:3584
	s_ashr_i32 s19, s18, 31
	s_add_i32 s22, s4, 3
	s_lshl_b64 s[18:19], s[18:19], 12
	s_ashr_i32 s23, s22, 31
	v_lshl_add_u64 v[56:57], v[20:21], 0, s[18:19]
	s_lshl_b64 s[22:23], s[22:23], 12
	global_load_dwordx2 v[68:69], v[56:57], off
	global_load_dwordx2 v[70:71], v[56:57], off offset:512
	global_load_dwordx2 v[72:73], v[56:57], off offset:1024
	global_load_dwordx2 v[74:75], v[56:57], off offset:1536
	global_load_dwordx2 v[94:95], v[56:57], off offset:2048
	global_load_dwordx2 v[96:97], v[56:57], off offset:2560
	global_load_dwordx2 v[98:99], v[56:57], off offset:3072
	global_load_dwordx2 v[106:107], v[56:57], off offset:3584
	v_lshl_add_u64 v[56:57], v[20:21], 0, s[22:23]
	global_load_dwordx2 v[128:129], v[56:57], off
	global_load_dwordx2 v[130:131], v[56:57], off offset:512
	global_load_dwordx2 v[146:147], v[56:57], off offset:1024
	global_load_dwordx2 v[164:165], v[56:57], off offset:1536
	global_load_dwordx2 v[166:167], v[56:57], off offset:2048
	global_load_dwordx2 v[168:169], v[56:57], off offset:2560
	global_load_dwordx2 v[170:171], v[56:57], off offset:3072
	global_load_dwordx2 v[176:177], v[56:57], off offset:3584
	s_ashr_i32 s5, s4, 31
	s_lshr_b32 s5, s5, 20
	s_add_i32 s5, s4, s5
	s_ashr_i32 s5, s5, 12
	v_mad_i64_i32 v[230:231], vcc, s5, v237, v[22:23]
	v_mad_i64_i32 v[192:193], vcc, s5, v237, v[24:25]
	v_lshl_add_u64 v[250:251], v[230:231], 0, s[86:87]
	v_lshl_add_u64 v[252:253], v[192:193], 0, s[86:87]
	global_load_dwordx4 v[180:183], v[8:9], off
	global_load_dwordx4 v[184:187], v[230:231], off
	global_load_dwordx4 v[188:191], v[192:193], off
	global_load_dwordx4 v[196:199], v[8:9], off offset:1024
	global_load_dwordx4 v[200:203], v[230:231], off offset:1024
	global_load_dwordx4 v[204:207], v[192:193], off offset:1024
	global_load_dwordx4 v[208:211], v[8:9], off offset:2048
	global_load_dwordx4 v[212:215], v[230:231], off offset:2048
	global_load_dwordx4 v[218:221], v[192:193], off offset:2048
	global_load_dwordx4 v[222:225], v[8:9], off offset:3072
	global_load_dwordx4 v[226:229], v[230:231], off offset:3072
	global_load_dwordx4 v[242:245], v[192:193], off offset:3072
	s_add_i32 s4, s4, s6
	s_cmp_lt_i32 s4, s20
	s_waitcnt vmcnt(43)
	v_cvt_f32_f16_sdwa v163, v2 dst_sel:DWORD dst_unused:UNUSED_PAD src0_sel:WORD_1
	s_waitcnt vmcnt(42)
	v_cvt_f32_f16_sdwa v135, v4 dst_sel:DWORD dst_unused:UNUSED_PAD src0_sel:WORD_1
	v_cvt_f32_f16_sdwa v101, v3 dst_sel:DWORD dst_unused:UNUSED_PAD src0_sel:WORD_1
	v_cvt_f32_f16_e32 v162, v2
	v_cvt_f32_f16_sdwa v133, v5 dst_sel:DWORD dst_unused:UNUSED_PAD src0_sel:WORD_1
	v_cvt_f32_f16_e32 v134, v4
	v_cvt_f32_f16_e32 v100, v3
	v_cvt_f32_f16_e32 v132, v5
	s_waitcnt vmcnt(41)
	v_cvt_f32_f16_e32 v116, v6
	v_cvt_f32_f16_sdwa v117, v6 dst_sel:DWORD dst_unused:UNUSED_PAD src0_sel:WORD_1
	v_cvt_f32_f16_e32 v118, v7
	v_cvt_f32_f16_sdwa v119, v7 dst_sel:DWORD dst_unused:UNUSED_PAD src0_sel:WORD_1
	v_mov_b32_e32 v2, v163
	v_mov_b32_e32 v3, v135
	s_waitcnt vmcnt(40)
	v_cvt_f32_f16_e32 v108, v28
	v_cvt_f32_f16_sdwa v109, v28 dst_sel:DWORD dst_unused:UNUSED_PAD src0_sel:WORD_1
	v_cvt_f32_f16_e32 v110, v29
	v_cvt_f32_f16_sdwa v111, v29 dst_sel:DWORD dst_unused:UNUSED_PAD src0_sel:WORD_1
	s_waitcnt vmcnt(39)
	v_cvt_f32_f16_sdwa v87, v31 dst_sel:DWORD dst_unused:UNUSED_PAD src0_sel:WORD_1
	v_cvt_f32_f16_e32 v86, v31
	v_cvt_f32_f16_sdwa v85, v30 dst_sel:DWORD dst_unused:UNUSED_PAD src0_sel:WORD_1
	v_cvt_f32_f16_e32 v84, v30
	s_waitcnt vmcnt(36)
	v_cvt_f32_f16_sdwa v29, v1 dst_sel:DWORD dst_unused:UNUSED_PAD src0_sel:WORD_1
	v_cvt_f32_f16_e32 v28, v1
	v_cvt_f32_f16_sdwa v31, v0 dst_sel:DWORD dst_unused:UNUSED_PAD src0_sel:WORD_1
	v_cvt_f32_f16_e32 v30, v0
	v_mov_b32_e32 v0, v162
	v_mov_b32_e32 v1, v134
	v_pk_mul_f32 v[2:3], v[2:3], v[2:3]
	v_mov_b32_e32 v4, v101
	v_mov_b32_e32 v5, v133
	v_pk_fma_f32 v[0:1], v[0:1], v[0:1], v[2:3]
	v_mov_b32_e32 v2, v100
	v_mov_b32_e32 v3, v132
	v_pk_mul_f32 v[4:5], v[4:5], v[4:5]
	v_cvt_f32_f16_e32 v80, v32
	v_pk_fma_f32 v[2:3], v[2:3], v[2:3], v[4:5]
	v_pk_mul_f32 v[4:5], v[116:117], v[116:117]
	v_pk_add_f32 v[0:1], v[0:1], v[2:3]
	v_pk_mul_f32 v[2:3], v[118:119], v[118:119]
	v_pk_add_f32 v[0:1], v[0:1], v[0:1] op_sel:[0,1] op_sel_hi:[1,0]
	v_pk_mov_b32 v[6:7], v[4:5], v[2:3] op_sel:[1,0]
	v_mov_b32_e32 v5, v3
	v_pk_add_f32 v[2:3], v[6:7], v[4:5]
	v_mul_f32_e32 v4, v84, v84
	v_mul_f32_e32 v5, v85, v85
	v_pk_add_f32 v[2:3], v[2:3], v[2:3] op_sel:[0,1] op_sel_hi:[1,0]
	v_mov_b32_e32 v1, v4
	v_mov_b32_e32 v3, v5
	v_cvt_f32_f16_sdwa v81, v32 dst_sel:DWORD dst_unused:UNUSED_PAD src0_sel:WORD_1
	v_cvt_f32_f16_e32 v82, v33
	v_cvt_f32_f16_sdwa v83, v33 dst_sel:DWORD dst_unused:UNUSED_PAD src0_sel:WORD_1
	v_pk_add_f32 v[0:1], v[0:1], v[2:3]
	v_mul_f32_e32 v2, v109, v109
	v_mul_f32_e32 v4, v111, v111
	v_mul_f32_e32 v6, v86, v86
	v_mul_f32_e32 v7, v87, v87
	v_pk_fma_f32 v[2:3], v[108:109], v[108:109], v[2:3] op_sel_hi:[1,1,0]
	v_pk_fma_f32 v[4:5], v[110:111], v[110:111], v[4:5] op_sel_hi:[1,1,0]
	v_mov_b32_e32 v3, v6
	v_mov_b32_e32 v5, v7
	v_pk_add_f32 v[2:3], v[2:3], v[4:5]
	v_pk_mul_f32 v[4:5], v[80:81], v[80:81]
	v_pk_add_f32 v[0:1], v[0:1], v[2:3]
	v_pk_mul_f32 v[2:3], v[82:83], v[82:83]
	v_cvt_f32_f16_sdwa v57, v34 dst_sel:DWORD dst_unused:UNUSED_PAD src0_sel:WORD_1
	v_cvt_f32_f16_sdwa v59, v35 dst_sel:DWORD dst_unused:UNUSED_PAD src0_sel:WORD_1
	v_pk_mov_b32 v[6:7], v[4:5], v[2:3] op_sel:[1,0]
	v_mov_b32_e32 v5, v3
	v_cvt_f32_f16_e32 v56, v34
	v_cvt_f32_f16_e32 v58, v35
	v_pk_add_f32 v[2:3], v[6:7], v[4:5]
	v_mul_f32_e32 v4, v30, v30
	v_mul_f32_e32 v5, v31, v31
	v_pk_add_f32 v[0:1], v[0:1], v[0:1] op_sel:[0,1] op_sel_hi:[1,0]
	v_pk_add_f32 v[2:3], v[2:3], v[2:3] op_sel:[0,1] op_sel_hi:[1,0]
	v_mov_b32_e32 v1, v4
	v_mov_b32_e32 v3, v5
	v_pk_add_f32 v[0:1], v[0:1], v[2:3]
	v_mul_f32_e32 v2, v57, v57
	v_mul_f32_e32 v4, v59, v59
	v_mul_f32_e32 v6, v28, v28
	v_mul_f32_e32 v7, v29, v29
	v_pk_fma_f32 v[2:3], v[56:57], v[56:57], v[2:3] op_sel_hi:[1,1,0]
	v_pk_fma_f32 v[4:5], v[58:59], v[58:59], v[4:5] op_sel_hi:[1,1,0]
	v_mov_b32_e32 v3, v6
	v_mov_b32_e32 v5, v7
	v_pk_add_f32 v[2:3], v[2:3], v[4:5]
	s_waitcnt vmcnt(35)
	v_cvt_f32_f16_sdwa v161, v38 dst_sel:DWORD dst_unused:UNUSED_PAD src0_sel:WORD_1
	v_pk_add_f32 v[0:1], v[0:1], v[2:3]
	s_waitcnt vmcnt(34)
	v_cvt_f32_f16_sdwa v143, v40 dst_sel:DWORD dst_unused:UNUSED_PAD src0_sel:WORD_1
	v_add_f32_e32 v0, v0, v1
	ds_bpermute_b32 v1, v45, v0
	v_cvt_f32_f16_sdwa v103, v39 dst_sel:DWORD dst_unused:UNUSED_PAD src0_sel:WORD_1
	v_cvt_f32_f16_e32 v160, v38
	v_cvt_f32_f16_sdwa v141, v41 dst_sel:DWORD dst_unused:UNUSED_PAD src0_sel:WORD_1
	v_cvt_f32_f16_e32 v142, v40
	s_waitcnt lgkmcnt(0)
	v_add_f32_e32 v0, v0, v1
	ds_bpermute_b32 v1, v55, v0
	v_cvt_f32_f16_e32 v102, v39
	v_cvt_f32_f16_e32 v140, v41
	s_waitcnt vmcnt(33)
	v_cvt_f32_f16_e32 v124, v42
	v_cvt_f32_f16_sdwa v125, v42 dst_sel:DWORD dst_unused:UNUSED_PAD src0_sel:WORD_1
	s_waitcnt lgkmcnt(0)
	v_add_f32_e32 v0, v0, v1
	ds_bpermute_b32 v1, v65, v0
	v_cvt_f32_f16_e32 v126, v43
	v_cvt_f32_f16_sdwa v127, v43 dst_sel:DWORD dst_unused:UNUSED_PAD src0_sel:WORD_1
	v_mov_b32_e32 v2, v161
	v_mov_b32_e32 v3, v143
	s_waitcnt lgkmcnt(0)
	v_add_f32_e32 v0, v0, v1
	ds_bpermute_b32 v1, v67, v0
	v_pk_mul_f32 v[2:3], v[2:3], v[2:3]
	v_mov_b32_e32 v4, v103
	v_mov_b32_e32 v5, v141
	v_pk_mul_f32 v[4:5], v[4:5], v[4:5]
	s_waitcnt lgkmcnt(0)
	v_add_f32_e32 v0, v0, v1
	ds_bpermute_b32 v1, v172, v0
	s_waitcnt vmcnt(31)
	v_cvt_f32_f16_sdwa v91, v48 dst_sel:DWORD dst_unused:UNUSED_PAD src0_sel:WORD_1
	v_cvt_f32_f16_e32 v90, v48
	v_cvt_f32_f16_sdwa v113, v46 dst_sel:DWORD dst_unused:UNUSED_PAD src0_sel:WORD_1
	v_cvt_f32_f16_sdwa v115, v47 dst_sel:DWORD dst_unused:UNUSED_PAD src0_sel:WORD_1
	s_waitcnt lgkmcnt(0)
	v_add_f32_e32 v0, v0, v1
	ds_bpermute_b32 v1, v173, v0
	v_cvt_f32_f16_e32 v112, v46
	v_cvt_f32_f16_e32 v114, v47
	v_cvt_f32_f16_sdwa v89, v49 dst_sel:DWORD dst_unused:UNUSED_PAD src0_sel:WORD_1
	v_cvt_f32_f16_e32 v88, v49
	s_waitcnt lgkmcnt(0)
	v_add_f32_e32 v0, v0, v1
	v_fmamk_f32 v0, v0, 0x3a000000, v232
	v_rsq_f32_e32 v44, v0
	v_mov_b32_e32 v0, v160
	v_mov_b32_e32 v1, v142
	v_pk_fma_f32 v[0:1], v[0:1], v[0:1], v[2:3]
	v_mov_b32_e32 v2, v102
	v_mov_b32_e32 v3, v140
	v_pk_fma_f32 v[2:3], v[2:3], v[2:3], v[4:5]
	v_pk_mul_f32 v[4:5], v[124:125], v[124:125]
	v_pk_add_f32 v[0:1], v[0:1], v[2:3]
	v_pk_mul_f32 v[2:3], v[126:127], v[126:127]
	v_pk_add_f32 v[0:1], v[0:1], v[0:1] op_sel:[0,1] op_sel_hi:[1,0]
	v_pk_mov_b32 v[6:7], v[4:5], v[2:3] op_sel:[1,0]
	v_mov_b32_e32 v5, v3
	v_pk_add_f32 v[2:3], v[6:7], v[4:5]
	v_mul_f32_e32 v4, v90, v90
	v_mul_f32_e32 v5, v91, v91
	v_pk_add_f32 v[2:3], v[2:3], v[2:3] op_sel:[0,1] op_sel_hi:[1,0]
	v_mov_b32_e32 v1, v4
	v_mov_b32_e32 v3, v5
	s_waitcnt vmcnt(30)
	v_cvt_f32_f16_e32 v76, v50
	v_cvt_f32_f16_sdwa v77, v50 dst_sel:DWORD dst_unused:UNUSED_PAD src0_sel:WORD_1
	v_cvt_f32_f16_e32 v78, v51
	v_cvt_f32_f16_sdwa v79, v51 dst_sel:DWORD dst_unused:UNUSED_PAD src0_sel:WORD_1
	v_pk_add_f32 v[0:1], v[0:1], v[2:3]
	v_mul_f32_e32 v2, v113, v113
	v_mul_f32_e32 v4, v115, v115
	v_mul_f32_e32 v6, v88, v88
	v_mul_f32_e32 v7, v89, v89
	v_pk_fma_f32 v[2:3], v[112:113], v[112:113], v[2:3] op_sel_hi:[1,1,0]
	v_pk_fma_f32 v[4:5], v[114:115], v[114:115], v[4:5] op_sel_hi:[1,1,0]
	v_mov_b32_e32 v3, v6
	v_mov_b32_e32 v5, v7
	s_waitcnt vmcnt(28)
	v_cvt_f32_f16_sdwa v35, v36 dst_sel:DWORD dst_unused:UNUSED_PAD src0_sel:WORD_1
	v_cvt_f32_f16_e32 v34, v36
	v_pk_add_f32 v[2:3], v[2:3], v[4:5]
	v_pk_mul_f32 v[4:5], v[76:77], v[76:77]
	v_pk_add_f32 v[0:1], v[0:1], v[2:3]
	v_pk_mul_f32 v[2:3], v[78:79], v[78:79]
	v_cvt_f32_f16_sdwa v61, v52 dst_sel:DWORD dst_unused:UNUSED_PAD src0_sel:WORD_1
	v_cvt_f32_f16_sdwa v63, v53 dst_sel:DWORD dst_unused:UNUSED_PAD src0_sel:WORD_1
	v_pk_mov_b32 v[6:7], v[4:5], v[2:3] op_sel:[1,0]
	v_mov_b32_e32 v5, v3
	v_cvt_f32_f16_e32 v60, v52
	v_cvt_f32_f16_e32 v62, v53
	v_cvt_f32_f16_sdwa v33, v37 dst_sel:DWORD dst_unused:UNUSED_PAD src0_sel:WORD_1
	v_cvt_f32_f16_e32 v32, v37
	v_pk_add_f32 v[2:3], v[6:7], v[4:5]
	v_mul_f32_e32 v4, v34, v34
	v_mul_f32_e32 v5, v35, v35
	v_pk_add_f32 v[0:1], v[0:1], v[0:1] op_sel:[0,1] op_sel_hi:[1,0]
	v_pk_add_f32 v[2:3], v[2:3], v[2:3] op_sel:[0,1] op_sel_hi:[1,0]
	v_mov_b32_e32 v1, v4
	v_mov_b32_e32 v3, v5
	v_pk_add_f32 v[0:1], v[0:1], v[2:3]
	v_mul_f32_e32 v2, v61, v61
	v_mul_f32_e32 v4, v63, v63
	v_mul_f32_e32 v6, v32, v32
	v_mul_f32_e32 v7, v33, v33
	v_pk_fma_f32 v[2:3], v[60:61], v[60:61], v[2:3] op_sel_hi:[1,1,0]
	v_pk_fma_f32 v[4:5], v[62:63], v[62:63], v[4:5] op_sel_hi:[1,1,0]
	v_mov_b32_e32 v3, v6
	v_mov_b32_e32 v5, v7
	v_pk_add_f32 v[2:3], v[2:3], v[4:5]
	s_waitcnt vmcnt(27)
	v_cvt_f32_f16_sdwa v159, v68 dst_sel:DWORD dst_unused:UNUSED_PAD src0_sel:WORD_1
	v_pk_add_f32 v[0:1], v[0:1], v[2:3]
	s_waitcnt vmcnt(26)
	v_cvt_f32_f16_sdwa v151, v70 dst_sel:DWORD dst_unused:UNUSED_PAD src0_sel:WORD_1
	v_add_f32_e32 v0, v0, v1
	ds_bpermute_b32 v1, v45, v0
	v_cvt_f32_f16_sdwa v105, v69 dst_sel:DWORD dst_unused:UNUSED_PAD src0_sel:WORD_1
	v_cvt_f32_f16_e32 v158, v68
	v_cvt_f32_f16_sdwa v149, v71 dst_sel:DWORD dst_unused:UNUSED_PAD src0_sel:WORD_1
	v_cvt_f32_f16_e32 v150, v70
	s_waitcnt lgkmcnt(0)
	v_add_f32_e32 v0, v0, v1
	ds_bpermute_b32 v1, v55, v0
	v_cvt_f32_f16_e32 v104, v69
	v_cvt_f32_f16_e32 v148, v71
	s_waitcnt vmcnt(25)
	v_cvt_f32_f16_e32 v136, v72
	v_cvt_f32_f16_sdwa v137, v72 dst_sel:DWORD dst_unused:UNUSED_PAD src0_sel:WORD_1
	s_waitcnt lgkmcnt(0)
	v_add_f32_e32 v0, v0, v1
	ds_bpermute_b32 v1, v65, v0
	v_cvt_f32_f16_e32 v138, v73
	v_cvt_f32_f16_sdwa v139, v73 dst_sel:DWORD dst_unused:UNUSED_PAD src0_sel:WORD_1
	v_mov_b32_e32 v2, v159
	v_mov_b32_e32 v3, v151
	s_waitcnt lgkmcnt(0)
	v_add_f32_e32 v0, v0, v1
	ds_bpermute_b32 v1, v67, v0
	v_pk_mul_f32 v[2:3], v[2:3], v[2:3]
	v_mov_b32_e32 v4, v105
	v_mov_b32_e32 v5, v149
	v_pk_mul_f32 v[4:5], v[4:5], v[4:5]
	s_waitcnt lgkmcnt(0)
	v_add_f32_e32 v0, v0, v1
	ds_bpermute_b32 v1, v172, v0
	s_waitcnt vmcnt(23)
	v_cvt_f32_f16_sdwa v93, v95 dst_sel:DWORD dst_unused:UNUSED_PAD src0_sel:WORD_1
	v_cvt_f32_f16_e32 v92, v95
	v_cvt_f32_f16_sdwa v95, v94 dst_sel:DWORD dst_unused:UNUSED_PAD src0_sel:WORD_1
	v_cvt_f32_f16_e32 v94, v94
	s_waitcnt lgkmcnt(0)
	v_add_f32_e32 v0, v0, v1
	ds_bpermute_b32 v1, v173, v0
	v_cvt_f32_f16_sdwa v121, v74 dst_sel:DWORD dst_unused:UNUSED_PAD src0_sel:WORD_1
	v_cvt_f32_f16_sdwa v123, v75 dst_sel:DWORD dst_unused:UNUSED_PAD src0_sel:WORD_1
	v_cvt_f32_f16_e32 v120, v74
	v_cvt_f32_f16_e32 v122, v75
	s_waitcnt lgkmcnt(0)
	v_add_f32_e32 v0, v0, v1
	v_fmamk_f32 v0, v0, 0x3a000000, v232
	v_rsq_f32_e32 v54, v0
	v_mov_b32_e32 v0, v158
	v_mov_b32_e32 v1, v150
	v_pk_fma_f32 v[0:1], v[0:1], v[0:1], v[2:3]
	v_mov_b32_e32 v2, v104
	v_mov_b32_e32 v3, v148
	v_pk_fma_f32 v[2:3], v[2:3], v[2:3], v[4:5]
	v_pk_mul_f32 v[4:5], v[136:137], v[136:137]
	v_pk_add_f32 v[0:1], v[0:1], v[2:3]
	v_pk_mul_f32 v[2:3], v[138:139], v[138:139]
	v_pk_add_f32 v[0:1], v[0:1], v[0:1] op_sel:[0,1] op_sel_hi:[1,0]
	v_pk_mov_b32 v[6:7], v[4:5], v[2:3] op_sel:[1,0]
	v_mov_b32_e32 v5, v3
	v_pk_add_f32 v[2:3], v[6:7], v[4:5]
	v_mul_f32_e32 v4, v94, v94
	v_mul_f32_e32 v5, v95, v95
	v_pk_add_f32 v[2:3], v[2:3], v[2:3] op_sel:[0,1] op_sel_hi:[1,0]
	v_mov_b32_e32 v1, v4
	v_mov_b32_e32 v3, v5
	s_waitcnt vmcnt(22)
	v_cvt_f32_f16_e32 v72, v96
	v_cvt_f32_f16_sdwa v73, v96 dst_sel:DWORD dst_unused:UNUSED_PAD src0_sel:WORD_1
	v_cvt_f32_f16_e32 v74, v97
	v_cvt_f32_f16_sdwa v75, v97 dst_sel:DWORD dst_unused:UNUSED_PAD src0_sel:WORD_1
	v_pk_add_f32 v[0:1], v[0:1], v[2:3]
	v_mul_f32_e32 v2, v121, v121
	v_mul_f32_e32 v4, v123, v123
	v_mul_f32_e32 v6, v92, v92
	v_mul_f32_e32 v7, v93, v93
	v_pk_fma_f32 v[2:3], v[120:121], v[120:121], v[2:3] op_sel_hi:[1,1,0]
	v_pk_fma_f32 v[4:5], v[122:123], v[122:123], v[4:5] op_sel_hi:[1,1,0]
	v_mov_b32_e32 v3, v6
	v_mov_b32_e32 v5, v7
	s_waitcnt vmcnt(20)
	v_cvt_f32_f16_sdwa v39, v106 dst_sel:DWORD dst_unused:UNUSED_PAD src0_sel:WORD_1
	v_cvt_f32_f16_e32 v38, v106
	v_pk_add_f32 v[2:3], v[2:3], v[4:5]
	v_pk_mul_f32 v[4:5], v[72:73], v[72:73]
	v_pk_add_f32 v[0:1], v[0:1], v[2:3]
	v_pk_mul_f32 v[2:3], v[74:75], v[74:75]
	v_cvt_f32_f16_sdwa v51, v98 dst_sel:DWORD dst_unused:UNUSED_PAD src0_sel:WORD_1
	v_cvt_f32_f16_sdwa v53, v99 dst_sel:DWORD dst_unused:UNUSED_PAD src0_sel:WORD_1
	v_pk_mov_b32 v[6:7], v[4:5], v[2:3] op_sel:[1,0]
	v_mov_b32_e32 v5, v3
	v_cvt_f32_f16_e32 v50, v98
	v_cvt_f32_f16_e32 v52, v99
	v_cvt_f32_f16_sdwa v37, v107 dst_sel:DWORD dst_unused:UNUSED_PAD src0_sel:WORD_1
	v_cvt_f32_f16_e32 v36, v107
	v_pk_add_f32 v[2:3], v[6:7], v[4:5]
	v_mul_f32_e32 v4, v38, v38
	v_mul_f32_e32 v5, v39, v39
	v_pk_add_f32 v[0:1], v[0:1], v[0:1] op_sel:[0,1] op_sel_hi:[1,0]
	v_pk_add_f32 v[2:3], v[2:3], v[2:3] op_sel:[0,1] op_sel_hi:[1,0]
	v_mov_b32_e32 v1, v4
	v_mov_b32_e32 v3, v5
	v_pk_add_f32 v[0:1], v[0:1], v[2:3]
	v_mul_f32_e32 v2, v51, v51
	v_mul_f32_e32 v4, v53, v53
	v_mul_f32_e32 v6, v36, v36
	v_mul_f32_e32 v7, v37, v37
	v_pk_fma_f32 v[2:3], v[50:51], v[50:51], v[2:3] op_sel_hi:[1,1,0]
	v_pk_fma_f32 v[4:5], v[52:53], v[52:53], v[4:5] op_sel_hi:[1,1,0]
	v_mov_b32_e32 v3, v6
	v_mov_b32_e32 v5, v7
	v_pk_add_f32 v[2:3], v[2:3], v[4:5]
	s_waitcnt vmcnt(19)
	v_cvt_f32_f16_sdwa v157, v128 dst_sel:DWORD dst_unused:UNUSED_PAD src0_sel:WORD_1
	v_pk_add_f32 v[0:1], v[0:1], v[2:3]
	s_waitcnt vmcnt(18)
	v_cvt_f32_f16_sdwa v155, v130 dst_sel:DWORD dst_unused:UNUSED_PAD src0_sel:WORD_1
	v_add_f32_e32 v0, v0, v1
	ds_bpermute_b32 v1, v45, v0
	v_cvt_f32_f16_sdwa v107, v129 dst_sel:DWORD dst_unused:UNUSED_PAD src0_sel:WORD_1
	v_cvt_f32_f16_e32 v156, v128
	v_cvt_f32_f16_sdwa v153, v131 dst_sel:DWORD dst_unused:UNUSED_PAD src0_sel:WORD_1
	v_cvt_f32_f16_e32 v154, v130
	s_waitcnt lgkmcnt(0)
	v_add_f32_e32 v0, v0, v1
	ds_bpermute_b32 v1, v55, v0
	v_cvt_f32_f16_e32 v106, v129
	v_cvt_f32_f16_e32 v152, v131
	s_waitcnt vmcnt(17)
	v_cvt_f32_f16_e32 v144, v146
	v_cvt_f32_f16_sdwa v145, v146 dst_sel:DWORD dst_unused:UNUSED_PAD src0_sel:WORD_1
	s_waitcnt lgkmcnt(0)
	v_add_f32_e32 v0, v0, v1
	ds_bpermute_b32 v1, v65, v0
	v_cvt_f32_f16_e32 v146, v147
	v_cvt_f32_f16_sdwa v147, v147 dst_sel:DWORD dst_unused:UNUSED_PAD src0_sel:WORD_1
	v_mov_b32_e32 v2, v157
	v_mov_b32_e32 v3, v155
	s_waitcnt lgkmcnt(0)
	v_add_f32_e32 v0, v0, v1
	ds_bpermute_b32 v1, v67, v0
	v_pk_mul_f32 v[2:3], v[2:3], v[2:3]
	v_mov_b32_e32 v4, v107
	v_mov_b32_e32 v5, v153
	v_pk_mul_f32 v[4:5], v[4:5], v[4:5]
	s_waitcnt lgkmcnt(0)
	v_add_f32_e32 v0, v0, v1
	ds_bpermute_b32 v1, v172, v0
	s_waitcnt vmcnt(15)
	v_cvt_f32_f16_sdwa v99, v166 dst_sel:DWORD dst_unused:UNUSED_PAD src0_sel:WORD_1
	v_cvt_f32_f16_e32 v98, v166
	v_cvt_f32_f16_sdwa v129, v164 dst_sel:DWORD dst_unused:UNUSED_PAD src0_sel:WORD_1
	v_cvt_f32_f16_sdwa v131, v165 dst_sel:DWORD dst_unused:UNUSED_PAD src0_sel:WORD_1
	s_waitcnt lgkmcnt(0)
	v_add_f32_e32 v0, v0, v1
	ds_bpermute_b32 v1, v173, v0
	v_cvt_f32_f16_e32 v128, v164
	v_cvt_f32_f16_e32 v130, v165
	v_cvt_f32_f16_sdwa v97, v167 dst_sel:DWORD dst_unused:UNUSED_PAD src0_sel:WORD_1
	v_cvt_f32_f16_e32 v96, v167
	s_waitcnt lgkmcnt(0)
	v_add_f32_e32 v0, v0, v1
	v_fmamk_f32 v0, v0, 0x3a000000, v232
	v_rsq_f32_e32 v64, v0
	v_mov_b32_e32 v0, v156
	v_mov_b32_e32 v1, v154
	v_pk_fma_f32 v[0:1], v[0:1], v[0:1], v[2:3]
	v_mov_b32_e32 v2, v106
	v_mov_b32_e32 v3, v152
	v_pk_fma_f32 v[2:3], v[2:3], v[2:3], v[4:5]
	v_pk_mul_f32 v[4:5], v[144:145], v[144:145]
	v_pk_add_f32 v[0:1], v[0:1], v[2:3]
	v_pk_mul_f32 v[2:3], v[146:147], v[146:147]
	v_pk_add_f32 v[0:1], v[0:1], v[0:1] op_sel:[0,1] op_sel_hi:[1,0]
	v_pk_mov_b32 v[6:7], v[4:5], v[2:3] op_sel:[1,0]
	v_mov_b32_e32 v5, v3
	v_pk_add_f32 v[2:3], v[6:7], v[4:5]
	v_mul_f32_e32 v4, v98, v98
	v_mul_f32_e32 v5, v99, v99
	v_pk_add_f32 v[2:3], v[2:3], v[2:3] op_sel:[0,1] op_sel_hi:[1,0]
	v_mov_b32_e32 v1, v4
	v_mov_b32_e32 v3, v5
	s_waitcnt vmcnt(14)
	v_cvt_f32_f16_e32 v68, v168
	v_cvt_f32_f16_sdwa v69, v168 dst_sel:DWORD dst_unused:UNUSED_PAD src0_sel:WORD_1
	v_cvt_f32_f16_e32 v70, v169
	v_cvt_f32_f16_sdwa v71, v169 dst_sel:DWORD dst_unused:UNUSED_PAD src0_sel:WORD_1
	v_pk_add_f32 v[0:1], v[0:1], v[2:3]
	v_mul_f32_e32 v2, v129, v129
	v_mul_f32_e32 v4, v131, v131
	v_mul_f32_e32 v6, v96, v96
	v_mul_f32_e32 v7, v97, v97
	v_pk_fma_f32 v[2:3], v[128:129], v[128:129], v[2:3] op_sel_hi:[1,1,0]
	v_pk_fma_f32 v[4:5], v[130:131], v[130:131], v[4:5] op_sel_hi:[1,1,0]
	v_mov_b32_e32 v3, v6
	v_mov_b32_e32 v5, v7
	s_waitcnt vmcnt(12)
	v_cvt_f32_f16_sdwa v43, v176 dst_sel:DWORD dst_unused:UNUSED_PAD src0_sel:WORD_1
	v_cvt_f32_f16_e32 v42, v176
	v_pk_add_f32 v[2:3], v[2:3], v[4:5]
	v_pk_mul_f32 v[4:5], v[68:69], v[68:69]
	v_pk_add_f32 v[0:1], v[0:1], v[2:3]
	v_pk_mul_f32 v[2:3], v[70:71], v[70:71]
	v_cvt_f32_f16_sdwa v47, v170 dst_sel:DWORD dst_unused:UNUSED_PAD src0_sel:WORD_1
	v_cvt_f32_f16_sdwa v49, v171 dst_sel:DWORD dst_unused:UNUSED_PAD src0_sel:WORD_1
	v_pk_mov_b32 v[6:7], v[4:5], v[2:3] op_sel:[1,0]
	v_mov_b32_e32 v5, v3
	v_cvt_f32_f16_e32 v46, v170
	v_cvt_f32_f16_e32 v48, v171
	v_cvt_f32_f16_sdwa v41, v177 dst_sel:DWORD dst_unused:UNUSED_PAD src0_sel:WORD_1
	v_cvt_f32_f16_e32 v40, v177
	v_pk_add_f32 v[2:3], v[6:7], v[4:5]
	v_mul_f32_e32 v4, v42, v42
	v_mul_f32_e32 v5, v43, v43
	v_pk_add_f32 v[0:1], v[0:1], v[0:1] op_sel:[0,1] op_sel_hi:[1,0]
	v_pk_add_f32 v[2:3], v[2:3], v[2:3] op_sel:[0,1] op_sel_hi:[1,0]
	v_mov_b32_e32 v1, v4
	v_mov_b32_e32 v3, v5
	v_pk_add_f32 v[0:1], v[0:1], v[2:3]
	v_mul_f32_e32 v2, v47, v47
	v_mul_f32_e32 v4, v49, v49
	v_mul_f32_e32 v6, v40, v40
	v_mul_f32_e32 v7, v41, v41
	v_pk_fma_f32 v[2:3], v[46:47], v[46:47], v[2:3] op_sel_hi:[1,1,0]
	v_pk_fma_f32 v[4:5], v[48:49], v[48:49], v[4:5] op_sel_hi:[1,1,0]
	v_mov_b32_e32 v3, v6
	v_mov_b32_e32 v5, v7
	v_pk_add_f32 v[2:3], v[2:3], v[4:5]
	v_mad_i64_i32 v[166:167], s[52:53], s5, v237, v[22:23]
	v_pk_add_f32 v[0:1], v[0:1], v[2:3]
	v_mad_i64_i32 v[164:165], s[52:53], s5, v237, v[24:25]
	v_add_f32_e32 v0, v0, v1
	ds_bpermute_b32 v1, v45, v0
	v_pk_mul_f32 v[100:101], v[44:45], v[100:101] op_sel_hi:[0,1]
	v_pk_mul_f32 v[162:163], v[44:45], v[162:163] op_sel_hi:[0,1]
	v_pk_mul_f32 v[102:103], v[54:55], v[102:103] op_sel_hi:[0,1]
	v_pk_mul_f32 v[160:161], v[54:55], v[160:161] op_sel_hi:[0,1]
	s_waitcnt lgkmcnt(0)
	v_add_f32_e32 v0, v0, v1
	ds_bpermute_b32 v1, v55, v0
	v_pk_mul_f32 v[104:105], v[64:65], v[104:105] op_sel_hi:[0,1]
	v_pk_mul_f32 v[158:159], v[64:65], v[158:159] op_sel_hi:[0,1]
	v_pk_mul_f32 v[132:133], v[44:45], v[132:133] op_sel_hi:[0,1]
	v_pk_mul_f32 v[134:135], v[44:45], v[134:135] op_sel_hi:[0,1]
	s_waitcnt lgkmcnt(0)
	v_add_f32_e32 v0, v0, v1
	ds_bpermute_b32 v1, v65, v0
	v_pk_mul_f32 v[118:119], v[44:45], v[118:119] op_sel_hi:[0,1]
	v_pk_mul_f32 v[116:117], v[44:45], v[116:117] op_sel_hi:[0,1]
	v_pk_mul_f32 v[110:111], v[44:45], v[110:111] op_sel_hi:[0,1]
	v_pk_mul_f32 v[108:109], v[44:45], v[108:109] op_sel_hi:[0,1]
	s_waitcnt lgkmcnt(0)
	v_add_f32_e32 v0, v0, v1
	ds_bpermute_b32 v1, v67, v0
	v_pk_mul_f32 v[86:87], v[44:45], v[86:87] op_sel_hi:[0,1]
	v_pk_mul_f32 v[84:85], v[44:45], v[84:85] op_sel_hi:[0,1]
	v_pk_mul_f32 v[82:83], v[44:45], v[82:83] op_sel_hi:[0,1]
	v_pk_mul_f32 v[80:81], v[44:45], v[80:81] op_sel_hi:[0,1]
	s_waitcnt lgkmcnt(0)
	v_add_f32_e32 v0, v0, v1
	ds_bpermute_b32 v1, v172, v0
	v_pk_mul_f32 v[78:79], v[54:55], v[78:79] op_sel_hi:[0,1]
	v_pk_mul_f32 v[76:77], v[54:55], v[76:77] op_sel_hi:[0,1]
	v_pk_mul_f32 v[74:75], v[64:65], v[74:75] op_sel_hi:[0,1]
	v_pk_mul_f32 v[72:73], v[64:65], v[72:73] op_sel_hi:[0,1]
	s_waitcnt lgkmcnt(0)
	v_add_f32_e32 v0, v0, v1
	ds_bpermute_b32 v1, v173, v0
	v_pk_mul_f32 v[58:59], v[44:45], v[58:59] op_sel_hi:[0,1]
	v_pk_mul_f32 v[56:57], v[44:45], v[56:57] op_sel_hi:[0,1]
	v_pk_mul_f32 v[52:53], v[64:65], v[52:53] op_sel_hi:[0,1]
	v_pk_mul_f32 v[50:51], v[64:65], v[50:51] op_sel_hi:[0,1]
	s_waitcnt lgkmcnt(0)
	v_add_f32_e32 v0, v0, v1
	v_fmamk_f32 v0, v0, 0x3a000000, v232
	v_rsq_f32_e32 v66, v0
	v_pk_mul_f32 v[28:29], v[44:45], v[28:29] op_sel_hi:[0,1]
	v_pk_mul_f32 v[30:31], v[44:45], v[30:31] op_sel_hi:[0,1]
	v_pk_mul_f32 v[106:107], v[66:67], v[106:107] op_sel_hi:[0,1]
	v_pk_mul_f32 v[156:157], v[66:67], v[156:157] op_sel_hi:[0,1]
	v_pk_mul_f32 v[70:71], v[66:67], v[70:71] op_sel_hi:[0,1]
	v_pk_mul_f32 v[68:69], v[66:67], v[68:69] op_sel_hi:[0,1]
	v_pk_mul_f32 v[48:49], v[66:67], v[48:49] op_sel_hi:[0,1]
	v_pk_mul_f32 v[46:47], v[66:67], v[46:47] op_sel_hi:[0,1]
	s_waitcnt vmcnt(9)
	v_pk_mul_f32 v[162:163], v[162:163], v[180:181]
	v_pk_mul_f32 v[100:101], v[100:101], v[182:183]
	v_pk_add_f32 v[168:169], v[190:191], 1.0 op_sel_hi:[1,0]
	v_pk_add_f32 v[170:171], v[188:189], 1.0 op_sel_hi:[1,0]
	v_pk_fma_f32 v[100:101], v[100:101], v[168:169], v[186:187]
	v_pk_fma_f32 v[162:163], v[162:163], v[170:171], v[184:185]
	v_pk_mul_f32 v[160:161], v[160:161], v[180:181]
	v_cvt_pk_bf16_f32 v162, v162, v163
	v_cvt_pk_bf16_f32 v163, v100, v101
	v_lshl_add_u64 v[100:101], s[14:15], 0, v[18:19]
	v_pk_mul_f32 v[102:103], v[102:103], v[182:183]
	v_add_co_u32_e32 v100, vcc, s30, v100
	v_pk_fma_f32 v[102:103], v[102:103], v[168:169], v[186:187]
	v_pk_fma_f32 v[160:161], v[160:161], v[170:171], v[184:185]
	v_addc_co_u32_e32 v101, vcc, 0, v101, vcc
	v_cvt_pk_bf16_f32 v160, v160, v161
	v_cvt_pk_bf16_f32 v161, v102, v103
	v_lshl_add_u64 v[102:103], s[8:9], 0, v[18:19]
	v_pk_mul_f32 v[158:159], v[180:181], v[158:159]
	v_pk_mul_f32 v[104:105], v[182:183], v[104:105]
	v_pk_mul_f32 v[180:181], v[180:181], v[156:157]
	v_pk_mul_f32 v[182:183], v[182:183], v[106:107]
	v_add_co_u32_e32 v102, vcc, s30, v102
	v_pk_fma_f32 v[104:105], v[104:105], v[168:169], v[186:187]
	v_pk_fma_f32 v[158:159], v[158:159], v[170:171], v[184:185]
	v_pk_fma_f32 v[186:187], v[168:169], v[182:183], v[186:187]
	v_pk_fma_f32 v[184:185], v[170:171], v[180:181], v[184:185]
	v_addc_co_u32_e32 v103, vcc, 0, v103, vcc
	v_cvt_pk_bf16_f32 v158, v158, v159
	v_cvt_pk_bf16_f32 v159, v104, v105
	v_lshl_add_u64 v[104:105], v[26:27], 0, s[18:19]
	v_cvt_pk_bf16_f32 v184, v184, v185
	v_cvt_pk_bf16_f32 v185, v186, v187
	v_lshl_add_u64 v[106:107], v[26:27], 0, s[22:23]
	global_store_dwordx2 v[100:101], v[162:163], off
	global_store_dwordx2 v[102:103], v[160:161], off
	global_store_dwordx2 v[104:105], v[158:159], off
	global_store_dwordx2 v[106:107], v[184:185], off
	global_load_dwordx4 v[180:183], v[10:11], off
	global_load_dwordx4 v[184:187], v[252:253], off
	global_load_dwordx4 v[188:191], v[250:251], off
	s_nop 0
	s_cselect_b64 s[18:19], -1, 0
	s_add_u32 s8, s8, s10
	s_addc_u32 s9, s9, s11
	s_add_u32 s12, s12, s10
	s_addc_u32 s13, s13, s11
	s_add_u32 s14, s14, s10
	s_addc_u32 s15, s15, s11
	s_add_u32 s16, s16, s10
	s_addc_u32 s17, s17, s11
	s_waitcnt vmcnt(13)
	v_pk_mul_f32 v[134:135], v[134:135], v[196:197]
	v_pk_mul_f32 v[132:133], v[132:133], v[198:199]
	v_pk_add_f32 v[206:207], v[206:207], 1.0 op_sel_hi:[1,0]
	v_pk_add_f32 v[204:205], v[204:205], 1.0 op_sel_hi:[1,0]
	v_pk_fma_f32 v[132:133], v[132:133], v[206:207], v[202:203]
	v_pk_fma_f32 v[134:135], v[134:135], v[204:205], v[200:201]
	s_nop 0
	v_cvt_pk_bf16_f32 v134, v134, v135
	v_cvt_pk_bf16_f32 v135, v132, v133
	global_store_dwordx2 v[100:101], v[134:135], off offset:512
	v_pk_mul_f32 v[132:133], v[54:55], v[140:141] op_sel_hi:[0,1]
	v_pk_mul_f32 v[134:135], v[54:55], v[142:143] op_sel_hi:[0,1]
	v_pk_mul_f32 v[134:135], v[134:135], v[196:197]
	v_pk_mul_f32 v[132:133], v[132:133], v[198:199]
	v_pk_fma_f32 v[134:135], v[134:135], v[204:205], v[200:201]
	v_pk_fma_f32 v[132:133], v[132:133], v[206:207], v[202:203]
	v_cvt_pk_bf16_f32 v134, v134, v135
	v_cvt_pk_bf16_f32 v135, v132, v133
	global_store_dwordx2 v[102:103], v[134:135], off offset:512
	v_pk_mul_f32 v[132:133], v[64:65], v[148:149] op_sel_hi:[0,1]
	v_pk_mul_f32 v[134:135], v[64:65], v[150:151] op_sel_hi:[0,1]
	v_pk_mul_f32 v[134:135], v[134:135], v[196:197]
	v_pk_mul_f32 v[132:133], v[132:133], v[198:199]
	v_pk_fma_f32 v[134:135], v[134:135], v[204:205], v[200:201]
	v_pk_fma_f32 v[132:133], v[132:133], v[206:207], v[202:203]
	v_cvt_pk_bf16_f32 v134, v134, v135
	v_cvt_pk_bf16_f32 v135, v132, v133
	global_store_dwordx2 v[104:105], v[134:135], off offset:512
	v_pk_mul_f32 v[132:133], v[66:67], v[152:153] op_sel_hi:[0,1]
	v_pk_mul_f32 v[134:135], v[66:67], v[154:155] op_sel_hi:[0,1]
	v_pk_mul_f32 v[196:197], v[196:197], v[134:135]
	v_pk_mul_f32 v[198:199], v[198:199], v[132:133]
	v_pk_fma_f32 v[196:197], v[196:197], v[204:205], v[200:201]
	v_pk_fma_f32 v[198:199], v[198:199], v[206:207], v[202:203]
	v_cvt_pk_bf16_f32 v196, v196, v197
	v_cvt_pk_bf16_f32 v197, v198, v199
	global_store_dwordx2 v[106:107], v[196:197], off offset:512
	global_load_dwordx4 v[196:199], v[12:13], off
	global_load_dwordx4 v[200:203], v[250:251], off offset:1024
	global_load_dwordx4 v[204:207], v[252:253], off offset:1024
	s_nop 0
	s_waitcnt vmcnt(17)
	v_pk_mul_f32 v[116:117], v[116:117], v[208:209]
	v_pk_mul_f32 v[118:119], v[118:119], v[210:211]
	v_pk_add_f32 v[220:221], v[220:221], 1.0 op_sel_hi:[1,0]
	v_pk_add_f32 v[218:219], v[218:219], 1.0 op_sel_hi:[1,0]
	v_pk_fma_f32 v[118:119], v[118:119], v[220:221], v[214:215]
	v_pk_fma_f32 v[116:117], v[116:117], v[218:219], v[212:213]
	s_nop 0
	v_cvt_pk_bf16_f32 v116, v116, v117
	v_cvt_pk_bf16_f32 v117, v118, v119
	global_store_dwordx2 v[100:101], v[116:117], off offset:1024
	v_pk_mul_f32 v[116:117], v[54:55], v[126:127] op_sel_hi:[0,1]
	v_pk_mul_f32 v[118:119], v[54:55], v[124:125] op_sel_hi:[0,1]
	v_pk_mul_f32 v[118:119], v[118:119], v[208:209]
	v_pk_mul_f32 v[116:117], v[116:117], v[210:211]
	v_pk_fma_f32 v[118:119], v[118:119], v[218:219], v[212:213]
	v_pk_fma_f32 v[116:117], v[116:117], v[220:221], v[214:215]
	v_cvt_pk_bf16_f32 v118, v118, v119
	v_cvt_pk_bf16_f32 v119, v116, v117
	global_store_dwordx2 v[102:103], v[118:119], off offset:1024
	v_pk_mul_f32 v[116:117], v[64:65], v[138:139] op_sel_hi:[0,1]
	v_pk_mul_f32 v[118:119], v[64:65], v[136:137] op_sel_hi:[0,1]
	v_pk_mul_f32 v[118:119], v[118:119], v[208:209]
	v_pk_mul_f32 v[116:117], v[116:117], v[210:211]
	v_pk_fma_f32 v[118:119], v[118:119], v[218:219], v[212:213]
	v_pk_fma_f32 v[116:117], v[116:117], v[220:221], v[214:215]
	v_cvt_pk_bf16_f32 v118, v118, v119
	v_cvt_pk_bf16_f32 v119, v116, v117
	global_store_dwordx2 v[104:105], v[118:119], off offset:1024
	v_pk_mul_f32 v[116:117], v[66:67], v[146:147] op_sel_hi:[0,1]
	v_pk_mul_f32 v[118:119], v[66:67], v[144:145] op_sel_hi:[0,1]
	v_pk_mul_f32 v[208:209], v[118:119], v[208:209]
	v_pk_mul_f32 v[210:211], v[116:117], v[210:211]
	v_pk_fma_f32 v[208:209], v[208:209], v[218:219], v[212:213]
	v_pk_fma_f32 v[210:211], v[210:211], v[220:221], v[214:215]
	v_cvt_pk_bf16_f32 v208, v208, v209
	v_cvt_pk_bf16_f32 v209, v210, v211
	global_store_dwordx2 v[106:107], v[208:209], off offset:1024
	global_load_dwordx4 v[208:211], v[14:15], off
	global_load_dwordx4 v[212:215], v[250:251], off offset:2048
	global_load_dwordx4 v[218:221], v[252:253], off offset:2048
	s_nop 0
	s_waitcnt vmcnt(21)
	v_pk_mul_f32 v[108:109], v[108:109], v[222:223]
	v_pk_mul_f32 v[110:111], v[110:111], v[224:225]
	v_pk_add_f32 v[244:245], v[244:245], 1.0 op_sel_hi:[1,0]
	v_pk_add_f32 v[242:243], v[242:243], 1.0 op_sel_hi:[1,0]
	v_pk_fma_f32 v[110:111], v[110:111], v[244:245], v[228:229]
	v_pk_fma_f32 v[108:109], v[108:109], v[242:243], v[226:227]
	s_nop 0
	v_cvt_pk_bf16_f32 v108, v108, v109
	v_cvt_pk_bf16_f32 v109, v110, v111
	global_store_dwordx2 v[100:101], v[108:109], off offset:1536
	v_pk_mul_f32 v[108:109], v[54:55], v[114:115] op_sel_hi:[0,1]
	v_pk_mul_f32 v[110:111], v[54:55], v[112:113] op_sel_hi:[0,1]
	v_pk_mul_f32 v[110:111], v[110:111], v[222:223]
	v_pk_mul_f32 v[108:109], v[108:109], v[224:225]
	v_pk_fma_f32 v[110:111], v[110:111], v[242:243], v[226:227]
	v_pk_fma_f32 v[108:109], v[108:109], v[244:245], v[228:229]
	v_cvt_pk_bf16_f32 v110, v110, v111
	v_cvt_pk_bf16_f32 v111, v108, v109
	global_store_dwordx2 v[102:103], v[110:111], off offset:1536
	v_pk_mul_f32 v[108:109], v[64:65], v[122:123] op_sel_hi:[0,1]
	v_pk_mul_f32 v[110:111], v[64:65], v[120:121] op_sel_hi:[0,1]
	v_pk_mul_f32 v[110:111], v[110:111], v[222:223]
	v_pk_mul_f32 v[108:109], v[108:109], v[224:225]
	v_pk_fma_f32 v[110:111], v[110:111], v[242:243], v[226:227]
	v_pk_fma_f32 v[108:109], v[108:109], v[244:245], v[228:229]
	v_cvt_pk_bf16_f32 v110, v110, v111
	v_cvt_pk_bf16_f32 v111, v108, v109
	global_store_dwordx2 v[104:105], v[110:111], off offset:1536
	v_pk_mul_f32 v[108:109], v[66:67], v[130:131] op_sel_hi:[0,1]
	v_pk_mul_f32 v[110:111], v[66:67], v[128:129] op_sel_hi:[0,1]
	v_pk_mul_f32 v[222:223], v[110:111], v[222:223]
	v_pk_mul_f32 v[224:225], v[108:109], v[224:225]
	v_add_co_u32_e32 v108, vcc, s77, v166
	v_pk_fma_f32 v[224:225], v[224:225], v[244:245], v[228:229]
	v_pk_fma_f32 v[222:223], v[222:223], v[242:243], v[226:227]
	v_addc_co_u32_e32 v109, vcc, 0, v167, vcc
	v_cvt_pk_bf16_f32 v222, v222, v223
	v_cvt_pk_bf16_f32 v223, v224, v225
	v_add_co_u32_e32 v110, vcc, s77, v164
	global_store_dwordx2 v[106:107], v[222:223], off offset:1536
	global_load_dwordx4 v[222:225], v[16:17], off
	global_load_dwordx4 v[226:229], v[250:251], off offset:3072
	global_load_dwordx4 v[242:245], v[252:253], off offset:3072
	s_nop 0
	v_addc_co_u32_e32 v111, vcc, 0, v165, vcc
	v_subrev_co_u32_e32 v174, vcc, 1, v174
	s_waitcnt vmcnt(21)
	v_pk_mul_f32 v[84:85], v[84:85], v[180:181]
	v_pk_add_f32 v[112:113], v[186:187], 1.0 op_sel_hi:[1,0]
	v_pk_add_f32 v[184:185], v[184:185], 1.0 op_sel_hi:[1,0]
	v_pk_mul_f32 v[86:87], v[86:87], v[182:183]
	v_pk_fma_f32 v[84:85], v[84:85], v[184:185], v[188:189]
	v_pk_fma_f32 v[86:87], v[86:87], v[112:113], v[190:191]
	v_cvt_pk_bf16_f32 v84, v84, v85
	v_cvt_pk_bf16_f32 v85, v86, v87
	global_store_dwordx2 v[100:101], v[84:85], off offset:2048
	v_pk_mul_f32 v[84:85], v[54:55], v[88:89] op_sel_hi:[0,1]
	v_pk_mul_f32 v[86:87], v[54:55], v[90:91] op_sel_hi:[0,1]
	v_pk_mul_f32 v[86:87], v[86:87], v[180:181]
	v_pk_mul_f32 v[84:85], v[84:85], v[182:183]
	v_pk_fma_f32 v[86:87], v[86:87], v[184:185], v[188:189]
	v_pk_fma_f32 v[84:85], v[84:85], v[112:113], v[190:191]
	v_cvt_pk_bf16_f32 v86, v86, v87
	v_cvt_pk_bf16_f32 v87, v84, v85
	global_store_dwordx2 v[102:103], v[86:87], off offset:2048
	v_pk_mul_f32 v[84:85], v[64:65], v[92:93] op_sel_hi:[0,1]
	v_pk_mul_f32 v[86:87], v[64:65], v[94:95] op_sel_hi:[0,1]
	v_pk_mul_f32 v[86:87], v[86:87], v[180:181]
	v_pk_mul_f32 v[84:85], v[84:85], v[182:183]
	v_pk_fma_f32 v[86:87], v[86:87], v[184:185], v[188:189]
	v_pk_fma_f32 v[84:85], v[84:85], v[112:113], v[190:191]
	v_cvt_pk_bf16_f32 v86, v86, v87
	v_cvt_pk_bf16_f32 v87, v84, v85
	global_store_dwordx2 v[104:105], v[86:87], off offset:2048
	v_pk_mul_f32 v[84:85], v[66:67], v[96:97] op_sel_hi:[0,1]
	v_pk_mul_f32 v[86:87], v[66:67], v[98:99] op_sel_hi:[0,1]
	v_pk_mul_f32 v[180:181], v[86:87], v[180:181]
	v_pk_mul_f32 v[182:183], v[84:85], v[182:183]
	v_pk_fma_f32 v[180:181], v[180:181], v[184:185], v[188:189]
	v_pk_fma_f32 v[182:183], v[182:183], v[112:113], v[190:191]
	v_cvt_pk_bf16_f32 v180, v180, v181
	v_cvt_pk_bf16_f32 v181, v182, v183
	global_store_dwordx2 v[106:107], v[180:181], off offset:2048
	s_nop 0
	s_waitcnt vmcnt(18)
	v_pk_mul_f32 v[80:81], v[80:81], v[196:197]
	v_pk_mul_f32 v[82:83], v[82:83], v[198:199]
	v_pk_add_f32 v[84:85], v[206:207], 1.0 op_sel_hi:[1,0]
	v_pk_add_f32 v[204:205], v[204:205], 1.0 op_sel_hi:[1,0]
	v_pk_mul_f32 v[76:77], v[76:77], v[196:197]
	v_pk_mul_f32 v[78:79], v[78:79], v[198:199]
	v_pk_mul_f32 v[72:73], v[72:73], v[196:197]
	v_pk_mul_f32 v[74:75], v[74:75], v[198:199]
	v_pk_mul_f32 v[196:197], v[68:69], v[196:197]
	v_pk_mul_f32 v[198:199], v[70:71], v[198:199]
	v_pk_fma_f32 v[82:83], v[82:83], v[84:85], v[202:203]
	v_pk_fma_f32 v[80:81], v[80:81], v[204:205], v[200:201]
	v_pk_fma_f32 v[78:79], v[78:79], v[84:85], v[202:203]
	v_pk_fma_f32 v[76:77], v[76:77], v[204:205], v[200:201]
	v_pk_fma_f32 v[74:75], v[74:75], v[84:85], v[202:203]
	v_pk_fma_f32 v[72:73], v[72:73], v[204:205], v[200:201]
	v_pk_fma_f32 v[202:203], v[198:199], v[84:85], v[202:203]
	v_pk_fma_f32 v[200:201], v[196:197], v[204:205], v[200:201]
	v_cvt_pk_bf16_f32 v80, v80, v81
	v_cvt_pk_bf16_f32 v81, v82, v83
	v_cvt_pk_bf16_f32 v76, v76, v77
	v_cvt_pk_bf16_f32 v77, v78, v79
	v_cvt_pk_bf16_f32 v72, v72, v73
	v_cvt_pk_bf16_f32 v73, v74, v75
	v_cvt_pk_bf16_f32 v200, v200, v201
	v_cvt_pk_bf16_f32 v201, v202, v203
	global_store_dwordx2 v[100:101], v[80:81], off offset:2560
	global_store_dwordx2 v[102:103], v[76:77], off offset:2560
	global_store_dwordx2 v[104:105], v[72:73], off offset:2560
	global_store_dwordx2 v[106:107], v[200:201], off offset:2560
	s_nop 0
	s_waitcnt vmcnt(15)
	v_pk_mul_f32 v[56:57], v[56:57], v[208:209]
	v_pk_mul_f32 v[58:59], v[58:59], v[210:211]
	v_pk_add_f32 v[220:221], v[220:221], 1.0 op_sel_hi:[1,0]
	v_pk_add_f32 v[218:219], v[218:219], 1.0 op_sel_hi:[1,0]
	v_pk_fma_f32 v[58:59], v[58:59], v[220:221], v[214:215]
	v_pk_fma_f32 v[56:57], v[56:57], v[218:219], v[212:213]
	v_pk_mul_f32 v[50:51], v[50:51], v[208:209]
	v_cvt_pk_bf16_f32 v56, v56, v57
	v_cvt_pk_bf16_f32 v57, v58, v59
	global_store_dwordx2 v[100:101], v[56:57], off offset:3072
	v_pk_mul_f32 v[56:57], v[54:55], v[62:63] op_sel_hi:[0,1]
	v_pk_mul_f32 v[58:59], v[54:55], v[60:61] op_sel_hi:[0,1]
	v_pk_mul_f32 v[58:59], v[58:59], v[208:209]
	v_pk_mul_f32 v[56:57], v[56:57], v[210:211]
	v_pk_mul_f32 v[52:53], v[52:53], v[210:211]
	v_pk_mul_f32 v[208:209], v[46:47], v[208:209]
	v_pk_mul_f32 v[210:211], v[48:49], v[210:211]
	v_pk_fma_f32 v[56:57], v[56:57], v[220:221], v[214:215]
	v_pk_fma_f32 v[58:59], v[58:59], v[218:219], v[212:213]
	v_pk_fma_f32 v[52:53], v[52:53], v[220:221], v[214:215]
	v_pk_fma_f32 v[50:51], v[50:51], v[218:219], v[212:213]
	v_pk_fma_f32 v[210:211], v[210:211], v[220:221], v[214:215]
	v_pk_fma_f32 v[208:209], v[208:209], v[218:219], v[212:213]
	v_cvt_pk_bf16_f32 v58, v58, v59
	v_cvt_pk_bf16_f32 v59, v56, v57
	v_cvt_pk_bf16_f32 v50, v50, v51
	v_cvt_pk_bf16_f32 v51, v52, v53
	v_cvt_pk_bf16_f32 v208, v208, v209
	v_cvt_pk_bf16_f32 v209, v210, v211
	global_store_dwordx2 v[102:103], v[58:59], off offset:3072
	global_store_dwordx2 v[104:105], v[50:51], off offset:3072
	global_store_dwordx2 v[106:107], v[208:209], off offset:3072
	s_nop 0
	s_waitcnt vmcnt(12)
	v_pk_mul_f32 v[30:31], v[30:31], v[222:223]
	v_pk_mul_f32 v[28:29], v[28:29], v[224:225]
	v_pk_add_f32 v[244:245], v[244:245], 1.0 op_sel_hi:[1,0]
	v_pk_add_f32 v[242:243], v[242:243], 1.0 op_sel_hi:[1,0]
	v_pk_fma_f32 v[28:29], v[28:29], v[244:245], v[228:229]
	v_pk_fma_f32 v[30:31], v[30:31], v[242:243], v[226:227]
	s_nop 0
	v_cvt_pk_bf16_f32 v30, v30, v31
	v_cvt_pk_bf16_f32 v31, v28, v29
	global_store_dwordx2 v[100:101], v[30:31], off offset:3584
	v_pk_mul_f32 v[28:29], v[54:55], v[32:33] op_sel_hi:[0,1]
	v_pk_mul_f32 v[30:31], v[54:55], v[34:35] op_sel_hi:[0,1]
	v_pk_mul_f32 v[30:31], v[30:31], v[222:223]
	v_pk_mul_f32 v[28:29], v[28:29], v[224:225]
	v_pk_fma_f32 v[30:31], v[30:31], v[242:243], v[226:227]
	v_pk_fma_f32 v[28:29], v[28:29], v[244:245], v[228:229]
	v_cvt_pk_bf16_f32 v30, v30, v31
	v_cvt_pk_bf16_f32 v31, v28, v29
	global_store_dwordx2 v[102:103], v[30:31], off offset:3584
	v_pk_mul_f32 v[28:29], v[64:65], v[36:37] op_sel_hi:[0,1]
	v_pk_mul_f32 v[30:31], v[64:65], v[38:39] op_sel_hi:[0,1]
	v_pk_mul_f32 v[30:31], v[30:31], v[222:223]
	v_pk_mul_f32 v[28:29], v[28:29], v[224:225]
	v_pk_fma_f32 v[30:31], v[30:31], v[242:243], v[226:227]
	v_pk_fma_f32 v[28:29], v[28:29], v[244:245], v[228:229]
	v_cvt_pk_bf16_f32 v30, v30, v31
	v_cvt_pk_bf16_f32 v31, v28, v29
	global_store_dwordx2 v[104:105], v[30:31], off offset:3584
	v_pk_mul_f32 v[28:29], v[66:67], v[40:41] op_sel_hi:[0,1]
	v_pk_mul_f32 v[30:31], v[66:67], v[42:43] op_sel_hi:[0,1]
	v_pk_mul_f32 v[222:223], v[30:31], v[222:223]
	v_pk_mul_f32 v[224:225], v[28:29], v[224:225]
	v_pk_fma_f32 v[222:223], v[222:223], v[242:243], v[226:227]
	v_pk_fma_f32 v[224:225], v[224:225], v[244:245], v[228:229]
	v_cvt_pk_bf16_f32 v222, v222, v223
	v_cvt_pk_bf16_f32 v223, v224, v225
	global_store_dwordx2 v[106:107], v[222:223], off offset:3584
	v_cndmask_b32_e64 v0, 0, 1, vcc
	v_cndmask_b32_e64 v1, 0, 1, s[18:19]
	v_cndmask_b32_e64 v0, v1, v0, s[2:3]
	v_and_b32_e32 v0, 1, v0
	v_cmp_eq_u32_e32 vcc, 1, v0
	s_cbranch_vccnz .LBB0_689

.LBB0_1793:
	v_lshl_add_u64 v[0:1], s[16:17], 0, v[18:19]
	v_add_co_u32_e32 v0, vcc, 0x3000000, v0
	v_lshl_add_u64 v[36:37], s[12:13], 0, v[18:19]
	s_nop 0
	v_addc_co_u32_e32 v1, vcc, 0, v1, vcc
	global_load_dwordx2 v[2:3], v[0:1], off
	global_load_dwordx2 v[4:5], v[0:1], off offset:512
	global_load_dwordx2 v[6:7], v[0:1], off offset:1024
	global_load_dwordx2 v[28:29], v[0:1], off offset:1536
	global_load_dwordx2 v[30:31], v[0:1], off offset:2048
	global_load_dwordx2 v[32:33], v[0:1], off offset:2560
	global_load_dwordx2 v[34:35], v[0:1], off offset:3072
	s_nop 0
	global_load_dwordx2 v[0:1], v[0:1], off offset:3584
	v_add_co_u32_e32 v36, vcc, 0x3000000, v36
	s_add_i32 s18, s4, 2
	s_nop 0
	v_addc_co_u32_e32 v37, vcc, 0, v37, vcc
	global_load_dwordx2 v[38:39], v[36:37], off
	global_load_dwordx2 v[40:41], v[36:37], off offset:512
	global_load_dwordx2 v[42:43], v[36:37], off offset:1024
	global_load_dwordx2 v[46:47], v[36:37], off offset:1536
	global_load_dwordx2 v[48:49], v[36:37], off offset:2048
	global_load_dwordx2 v[50:51], v[36:37], off offset:2560
	global_load_dwordx2 v[52:53], v[36:37], off offset:3072
	s_nop 0
	global_load_dwordx2 v[36:37], v[36:37], off offset:3584
	s_ashr_i32 s19, s18, 31
	s_add_i32 s22, s4, 3
	s_lshl_b64 s[18:19], s[18:19], 12
	s_ashr_i32 s23, s22, 31
	v_lshl_add_u64 v[56:57], v[20:21], 0, s[18:19]
	s_lshl_b64 s[22:23], s[22:23], 12
	global_load_dwordx2 v[68:69], v[56:57], off
	global_load_dwordx2 v[70:71], v[56:57], off offset:512
	global_load_dwordx2 v[72:73], v[56:57], off offset:1024
	global_load_dwordx2 v[74:75], v[56:57], off offset:1536
	global_load_dwordx2 v[94:95], v[56:57], off offset:2048
	global_load_dwordx2 v[96:97], v[56:57], off offset:2560
	global_load_dwordx2 v[98:99], v[56:57], off offset:3072
	global_load_dwordx2 v[106:107], v[56:57], off offset:3584
	v_lshl_add_u64 v[56:57], v[20:21], 0, s[22:23]
	global_load_dwordx2 v[128:129], v[56:57], off
	global_load_dwordx2 v[130:131], v[56:57], off offset:512
	global_load_dwordx2 v[146:147], v[56:57], off offset:1024
	global_load_dwordx2 v[164:165], v[56:57], off offset:1536
	global_load_dwordx2 v[166:167], v[56:57], off offset:2048
	global_load_dwordx2 v[168:169], v[56:57], off offset:2560
	global_load_dwordx2 v[170:171], v[56:57], off offset:3072
	global_load_dwordx2 v[176:177], v[56:57], off offset:3584
	s_ashr_i32 s5, s4, 31
	s_lshr_b32 s5, s5, 20
	s_add_i32 s5, s4, s5
	s_ashr_i32 s5, s5, 12
	v_mad_i64_i32 v[230:231], vcc, s5, v237, v[22:23]
	v_mad_i64_i32 v[192:193], vcc, s5, v237, v[24:25]
	v_lshl_add_u64 v[250:251], v[230:231], 0, s[86:87]
	v_lshl_add_u64 v[252:253], v[192:193], 0, s[86:87]
	global_load_dwordx4 v[180:183], v[8:9], off
	global_load_dwordx4 v[184:187], v[230:231], off
	global_load_dwordx4 v[188:191], v[192:193], off
	global_load_dwordx4 v[196:199], v[8:9], off offset:1024
	global_load_dwordx4 v[200:203], v[230:231], off offset:1024
	global_load_dwordx4 v[204:207], v[192:193], off offset:1024
	global_load_dwordx4 v[208:211], v[8:9], off offset:2048
	global_load_dwordx4 v[212:215], v[230:231], off offset:2048
	global_load_dwordx4 v[218:221], v[192:193], off offset:2048
	global_load_dwordx4 v[222:225], v[8:9], off offset:3072
	global_load_dwordx4 v[226:229], v[230:231], off offset:3072
	global_load_dwordx4 v[242:245], v[192:193], off offset:3072
	s_add_i32 s4, s4, s6
	s_cmp_lt_i32 s4, s20
	s_waitcnt vmcnt(43)
	v_cvt_f32_f16_sdwa v163, v2 dst_sel:DWORD dst_unused:UNUSED_PAD src0_sel:WORD_1
	s_waitcnt vmcnt(42)
	v_cvt_f32_f16_sdwa v135, v4 dst_sel:DWORD dst_unused:UNUSED_PAD src0_sel:WORD_1
	v_cvt_f32_f16_sdwa v101, v3 dst_sel:DWORD dst_unused:UNUSED_PAD src0_sel:WORD_1
	v_cvt_f32_f16_e32 v162, v2
	v_cvt_f32_f16_sdwa v133, v5 dst_sel:DWORD dst_unused:UNUSED_PAD src0_sel:WORD_1
	v_cvt_f32_f16_e32 v134, v4
	v_cvt_f32_f16_e32 v100, v3
	v_cvt_f32_f16_e32 v132, v5
	s_waitcnt vmcnt(41)
	v_cvt_f32_f16_e32 v116, v6
	v_cvt_f32_f16_sdwa v117, v6 dst_sel:DWORD dst_unused:UNUSED_PAD src0_sel:WORD_1
	v_cvt_f32_f16_e32 v118, v7
	v_cvt_f32_f16_sdwa v119, v7 dst_sel:DWORD dst_unused:UNUSED_PAD src0_sel:WORD_1
	v_mov_b32_e32 v2, v163
	v_mov_b32_e32 v3, v135
	s_waitcnt vmcnt(40)
	v_cvt_f32_f16_e32 v108, v28
	v_cvt_f32_f16_sdwa v109, v28 dst_sel:DWORD dst_unused:UNUSED_PAD src0_sel:WORD_1
	v_cvt_f32_f16_e32 v110, v29
	v_cvt_f32_f16_sdwa v111, v29 dst_sel:DWORD dst_unused:UNUSED_PAD src0_sel:WORD_1
	s_waitcnt vmcnt(39)
	v_cvt_f32_f16_sdwa v87, v31 dst_sel:DWORD dst_unused:UNUSED_PAD src0_sel:WORD_1
	v_cvt_f32_f16_e32 v86, v31
	v_cvt_f32_f16_sdwa v85, v30 dst_sel:DWORD dst_unused:UNUSED_PAD src0_sel:WORD_1
	v_cvt_f32_f16_e32 v84, v30
	s_waitcnt vmcnt(36)
	v_cvt_f32_f16_sdwa v29, v1 dst_sel:DWORD dst_unused:UNUSED_PAD src0_sel:WORD_1
	v_cvt_f32_f16_e32 v28, v1
	v_cvt_f32_f16_sdwa v31, v0 dst_sel:DWORD dst_unused:UNUSED_PAD src0_sel:WORD_1
	v_cvt_f32_f16_e32 v30, v0
	v_mov_b32_e32 v0, v162
	v_mov_b32_e32 v1, v134
	v_pk_mul_f32 v[2:3], v[2:3], v[2:3]
	v_mov_b32_e32 v4, v101
	v_mov_b32_e32 v5, v133
	v_pk_fma_f32 v[0:1], v[0:1], v[0:1], v[2:3]
	v_mov_b32_e32 v2, v100
	v_mov_b32_e32 v3, v132
	v_pk_mul_f32 v[4:5], v[4:5], v[4:5]
	v_cvt_f32_f16_e32 v80, v32
	v_pk_fma_f32 v[2:3], v[2:3], v[2:3], v[4:5]
	v_pk_mul_f32 v[4:5], v[116:117], v[116:117]
	v_pk_add_f32 v[0:1], v[0:1], v[2:3]
	v_pk_mul_f32 v[2:3], v[118:119], v[118:119]
	v_pk_add_f32 v[0:1], v[0:1], v[0:1] op_sel:[0,1] op_sel_hi:[1,0]
	v_pk_mov_b32 v[6:7], v[4:5], v[2:3] op_sel:[1,0]
	v_mov_b32_e32 v5, v3
	v_pk_add_f32 v[2:3], v[6:7], v[4:5]
	v_mul_f32_e32 v4, v84, v84
	v_mul_f32_e32 v5, v85, v85
	v_pk_add_f32 v[2:3], v[2:3], v[2:3] op_sel:[0,1] op_sel_hi:[1,0]
	v_mov_b32_e32 v1, v4
	v_mov_b32_e32 v3, v5
	v_cvt_f32_f16_sdwa v81, v32 dst_sel:DWORD dst_unused:UNUSED_PAD src0_sel:WORD_1
	v_cvt_f32_f16_e32 v82, v33
	v_cvt_f32_f16_sdwa v83, v33 dst_sel:DWORD dst_unused:UNUSED_PAD src0_sel:WORD_1
	v_pk_add_f32 v[0:1], v[0:1], v[2:3]
	v_mul_f32_e32 v2, v109, v109
	v_mul_f32_e32 v4, v111, v111
	v_mul_f32_e32 v6, v86, v86
	v_mul_f32_e32 v7, v87, v87
	v_pk_fma_f32 v[2:3], v[108:109], v[108:109], v[2:3] op_sel_hi:[1,1,0]
	v_pk_fma_f32 v[4:5], v[110:111], v[110:111], v[4:5] op_sel_hi:[1,1,0]
	v_mov_b32_e32 v3, v6
	v_mov_b32_e32 v5, v7
	v_pk_add_f32 v[2:3], v[2:3], v[4:5]
	v_pk_mul_f32 v[4:5], v[80:81], v[80:81]
	v_pk_add_f32 v[0:1], v[0:1], v[2:3]
	v_pk_mul_f32 v[2:3], v[82:83], v[82:83]
	v_cvt_f32_f16_sdwa v57, v34 dst_sel:DWORD dst_unused:UNUSED_PAD src0_sel:WORD_1
	v_cvt_f32_f16_sdwa v59, v35 dst_sel:DWORD dst_unused:UNUSED_PAD src0_sel:WORD_1
	v_pk_mov_b32 v[6:7], v[4:5], v[2:3] op_sel:[1,0]
	v_mov_b32_e32 v5, v3
	v_cvt_f32_f16_e32 v56, v34
	v_cvt_f32_f16_e32 v58, v35
	v_pk_add_f32 v[2:3], v[6:7], v[4:5]
	v_mul_f32_e32 v4, v30, v30
	v_mul_f32_e32 v5, v31, v31
	v_pk_add_f32 v[0:1], v[0:1], v[0:1] op_sel:[0,1] op_sel_hi:[1,0]
	v_pk_add_f32 v[2:3], v[2:3], v[2:3] op_sel:[0,1] op_sel_hi:[1,0]
	v_mov_b32_e32 v1, v4
	v_mov_b32_e32 v3, v5
	v_pk_add_f32 v[0:1], v[0:1], v[2:3]
	v_mul_f32_e32 v2, v57, v57
	v_mul_f32_e32 v4, v59, v59
	v_mul_f32_e32 v6, v28, v28
	v_mul_f32_e32 v7, v29, v29
	v_pk_fma_f32 v[2:3], v[56:57], v[56:57], v[2:3] op_sel_hi:[1,1,0]
	v_pk_fma_f32 v[4:5], v[58:59], v[58:59], v[4:5] op_sel_hi:[1,1,0]
	v_mov_b32_e32 v3, v6
	v_mov_b32_e32 v5, v7
	v_pk_add_f32 v[2:3], v[2:3], v[4:5]
	s_waitcnt vmcnt(35)
	v_cvt_f32_f16_sdwa v161, v38 dst_sel:DWORD dst_unused:UNUSED_PAD src0_sel:WORD_1
	v_pk_add_f32 v[0:1], v[0:1], v[2:3]
	s_waitcnt vmcnt(34)
	v_cvt_f32_f16_sdwa v143, v40 dst_sel:DWORD dst_unused:UNUSED_PAD src0_sel:WORD_1
	v_add_f32_e32 v0, v0, v1
	ds_bpermute_b32 v1, v45, v0
	v_cvt_f32_f16_sdwa v103, v39 dst_sel:DWORD dst_unused:UNUSED_PAD src0_sel:WORD_1
	v_cvt_f32_f16_e32 v160, v38
	v_cvt_f32_f16_sdwa v141, v41 dst_sel:DWORD dst_unused:UNUSED_PAD src0_sel:WORD_1
	v_cvt_f32_f16_e32 v142, v40
	s_waitcnt lgkmcnt(0)
	v_add_f32_e32 v0, v0, v1
	ds_bpermute_b32 v1, v55, v0
	v_cvt_f32_f16_e32 v102, v39
	v_cvt_f32_f16_e32 v140, v41
	s_waitcnt vmcnt(33)
	v_cvt_f32_f16_e32 v124, v42
	v_cvt_f32_f16_sdwa v125, v42 dst_sel:DWORD dst_unused:UNUSED_PAD src0_sel:WORD_1
	s_waitcnt lgkmcnt(0)
	v_add_f32_e32 v0, v0, v1
	ds_bpermute_b32 v1, v65, v0
	v_cvt_f32_f16_e32 v126, v43
	v_cvt_f32_f16_sdwa v127, v43 dst_sel:DWORD dst_unused:UNUSED_PAD src0_sel:WORD_1
	v_mov_b32_e32 v2, v161
	v_mov_b32_e32 v3, v143
	s_waitcnt lgkmcnt(0)
	v_add_f32_e32 v0, v0, v1
	ds_bpermute_b32 v1, v67, v0
	v_pk_mul_f32 v[2:3], v[2:3], v[2:3]
	v_mov_b32_e32 v4, v103
	v_mov_b32_e32 v5, v141
	v_pk_mul_f32 v[4:5], v[4:5], v[4:5]
	s_waitcnt lgkmcnt(0)
	v_add_f32_e32 v0, v0, v1
	ds_bpermute_b32 v1, v173, v0
	s_waitcnt vmcnt(31)
	v_cvt_f32_f16_sdwa v91, v48 dst_sel:DWORD dst_unused:UNUSED_PAD src0_sel:WORD_1
	v_cvt_f32_f16_e32 v90, v48
	v_cvt_f32_f16_sdwa v113, v46 dst_sel:DWORD dst_unused:UNUSED_PAD src0_sel:WORD_1
	v_cvt_f32_f16_sdwa v115, v47 dst_sel:DWORD dst_unused:UNUSED_PAD src0_sel:WORD_1
	s_waitcnt lgkmcnt(0)
	v_add_f32_e32 v0, v0, v1
	ds_bpermute_b32 v1, v174, v0
	v_cvt_f32_f16_e32 v112, v46
	v_cvt_f32_f16_e32 v114, v47
	v_cvt_f32_f16_sdwa v89, v49 dst_sel:DWORD dst_unused:UNUSED_PAD src0_sel:WORD_1
	v_cvt_f32_f16_e32 v88, v49
	s_waitcnt lgkmcnt(0)
	v_add_f32_e32 v0, v0, v1
	v_fmamk_f32 v0, v0, 0x3a000000, v232
	v_rsq_f32_e32 v44, v0
	v_mov_b32_e32 v0, v160
	v_mov_b32_e32 v1, v142
	v_pk_fma_f32 v[0:1], v[0:1], v[0:1], v[2:3]
	v_mov_b32_e32 v2, v102
	v_mov_b32_e32 v3, v140
	v_pk_fma_f32 v[2:3], v[2:3], v[2:3], v[4:5]
	v_pk_mul_f32 v[4:5], v[124:125], v[124:125]
	v_pk_add_f32 v[0:1], v[0:1], v[2:3]
	v_pk_mul_f32 v[2:3], v[126:127], v[126:127]
	v_pk_add_f32 v[0:1], v[0:1], v[0:1] op_sel:[0,1] op_sel_hi:[1,0]
	v_pk_mov_b32 v[6:7], v[4:5], v[2:3] op_sel:[1,0]
	v_mov_b32_e32 v5, v3
	v_pk_add_f32 v[2:3], v[6:7], v[4:5]
	v_mul_f32_e32 v4, v90, v90
	v_mul_f32_e32 v5, v91, v91
	v_pk_add_f32 v[2:3], v[2:3], v[2:3] op_sel:[0,1] op_sel_hi:[1,0]
	v_mov_b32_e32 v1, v4
	v_mov_b32_e32 v3, v5
	s_waitcnt vmcnt(30)
	v_cvt_f32_f16_e32 v76, v50
	v_cvt_f32_f16_sdwa v77, v50 dst_sel:DWORD dst_unused:UNUSED_PAD src0_sel:WORD_1
	v_cvt_f32_f16_e32 v78, v51
	v_cvt_f32_f16_sdwa v79, v51 dst_sel:DWORD dst_unused:UNUSED_PAD src0_sel:WORD_1
	v_pk_add_f32 v[0:1], v[0:1], v[2:3]
	v_mul_f32_e32 v2, v113, v113
	v_mul_f32_e32 v4, v115, v115
	v_mul_f32_e32 v6, v88, v88
	v_mul_f32_e32 v7, v89, v89
	v_pk_fma_f32 v[2:3], v[112:113], v[112:113], v[2:3] op_sel_hi:[1,1,0]
	v_pk_fma_f32 v[4:5], v[114:115], v[114:115], v[4:5] op_sel_hi:[1,1,0]
	v_mov_b32_e32 v3, v6
	v_mov_b32_e32 v5, v7
	s_waitcnt vmcnt(28)
	v_cvt_f32_f16_sdwa v35, v36 dst_sel:DWORD dst_unused:UNUSED_PAD src0_sel:WORD_1
	v_cvt_f32_f16_e32 v34, v36
	v_pk_add_f32 v[2:3], v[2:3], v[4:5]
	v_pk_mul_f32 v[4:5], v[76:77], v[76:77]
	v_pk_add_f32 v[0:1], v[0:1], v[2:3]
	v_pk_mul_f32 v[2:3], v[78:79], v[78:79]
	v_cvt_f32_f16_sdwa v61, v52 dst_sel:DWORD dst_unused:UNUSED_PAD src0_sel:WORD_1
	v_cvt_f32_f16_sdwa v63, v53 dst_sel:DWORD dst_unused:UNUSED_PAD src0_sel:WORD_1
	v_pk_mov_b32 v[6:7], v[4:5], v[2:3] op_sel:[1,0]
	v_mov_b32_e32 v5, v3
	v_cvt_f32_f16_e32 v60, v52
	v_cvt_f32_f16_e32 v62, v53
	v_cvt_f32_f16_sdwa v33, v37 dst_sel:DWORD dst_unused:UNUSED_PAD src0_sel:WORD_1
	v_cvt_f32_f16_e32 v32, v37
	v_pk_add_f32 v[2:3], v[6:7], v[4:5]
	v_mul_f32_e32 v4, v34, v34
	v_mul_f32_e32 v5, v35, v35
	v_pk_add_f32 v[0:1], v[0:1], v[0:1] op_sel:[0,1] op_sel_hi:[1,0]
	v_pk_add_f32 v[2:3], v[2:3], v[2:3] op_sel:[0,1] op_sel_hi:[1,0]
	v_mov_b32_e32 v1, v4
	v_mov_b32_e32 v3, v5
	v_pk_add_f32 v[0:1], v[0:1], v[2:3]
	v_mul_f32_e32 v2, v61, v61
	v_mul_f32_e32 v4, v63, v63
	v_mul_f32_e32 v6, v32, v32
	v_mul_f32_e32 v7, v33, v33
	v_pk_fma_f32 v[2:3], v[60:61], v[60:61], v[2:3] op_sel_hi:[1,1,0]
	v_pk_fma_f32 v[4:5], v[62:63], v[62:63], v[4:5] op_sel_hi:[1,1,0]
	v_mov_b32_e32 v3, v6
	v_mov_b32_e32 v5, v7
	v_pk_add_f32 v[2:3], v[2:3], v[4:5]
	s_waitcnt vmcnt(27)
	v_cvt_f32_f16_sdwa v159, v68 dst_sel:DWORD dst_unused:UNUSED_PAD src0_sel:WORD_1
	v_pk_add_f32 v[0:1], v[0:1], v[2:3]
	s_waitcnt vmcnt(26)
	v_cvt_f32_f16_sdwa v151, v70 dst_sel:DWORD dst_unused:UNUSED_PAD src0_sel:WORD_1
	v_add_f32_e32 v0, v0, v1
	ds_bpermute_b32 v1, v45, v0
	v_cvt_f32_f16_sdwa v105, v69 dst_sel:DWORD dst_unused:UNUSED_PAD src0_sel:WORD_1
	v_cvt_f32_f16_e32 v158, v68
	v_cvt_f32_f16_sdwa v149, v71 dst_sel:DWORD dst_unused:UNUSED_PAD src0_sel:WORD_1
	v_cvt_f32_f16_e32 v150, v70
	s_waitcnt lgkmcnt(0)
	v_add_f32_e32 v0, v0, v1
	ds_bpermute_b32 v1, v55, v0
	v_cvt_f32_f16_e32 v104, v69
	v_cvt_f32_f16_e32 v148, v71
	s_waitcnt vmcnt(25)
	v_cvt_f32_f16_e32 v136, v72
	v_cvt_f32_f16_sdwa v137, v72 dst_sel:DWORD dst_unused:UNUSED_PAD src0_sel:WORD_1
	s_waitcnt lgkmcnt(0)
	v_add_f32_e32 v0, v0, v1
	ds_bpermute_b32 v1, v65, v0
	v_cvt_f32_f16_e32 v138, v73
	v_cvt_f32_f16_sdwa v139, v73 dst_sel:DWORD dst_unused:UNUSED_PAD src0_sel:WORD_1
	v_mov_b32_e32 v2, v159
	v_mov_b32_e32 v3, v151
	s_waitcnt lgkmcnt(0)
	v_add_f32_e32 v0, v0, v1
	ds_bpermute_b32 v1, v67, v0
	v_pk_mul_f32 v[2:3], v[2:3], v[2:3]
	v_mov_b32_e32 v4, v105
	v_mov_b32_e32 v5, v149
	v_pk_mul_f32 v[4:5], v[4:5], v[4:5]
	s_waitcnt lgkmcnt(0)
	v_add_f32_e32 v0, v0, v1
	ds_bpermute_b32 v1, v173, v0
	s_waitcnt vmcnt(23)
	v_cvt_f32_f16_sdwa v93, v95 dst_sel:DWORD dst_unused:UNUSED_PAD src0_sel:WORD_1
	v_cvt_f32_f16_e32 v92, v95
	v_cvt_f32_f16_sdwa v95, v94 dst_sel:DWORD dst_unused:UNUSED_PAD src0_sel:WORD_1
	v_cvt_f32_f16_e32 v94, v94
	s_waitcnt lgkmcnt(0)
	v_add_f32_e32 v0, v0, v1
	ds_bpermute_b32 v1, v174, v0
	v_cvt_f32_f16_sdwa v121, v74 dst_sel:DWORD dst_unused:UNUSED_PAD src0_sel:WORD_1
	v_cvt_f32_f16_sdwa v123, v75 dst_sel:DWORD dst_unused:UNUSED_PAD src0_sel:WORD_1
	v_cvt_f32_f16_e32 v120, v74
	v_cvt_f32_f16_e32 v122, v75
	s_waitcnt lgkmcnt(0)
	v_add_f32_e32 v0, v0, v1
	v_fmamk_f32 v0, v0, 0x3a000000, v232
	v_rsq_f32_e32 v54, v0
	v_mov_b32_e32 v0, v158
	v_mov_b32_e32 v1, v150
	v_pk_fma_f32 v[0:1], v[0:1], v[0:1], v[2:3]
	v_mov_b32_e32 v2, v104
	v_mov_b32_e32 v3, v148
	v_pk_fma_f32 v[2:3], v[2:3], v[2:3], v[4:5]
	v_pk_mul_f32 v[4:5], v[136:137], v[136:137]
	v_pk_add_f32 v[0:1], v[0:1], v[2:3]
	v_pk_mul_f32 v[2:3], v[138:139], v[138:139]
	v_pk_add_f32 v[0:1], v[0:1], v[0:1] op_sel:[0,1] op_sel_hi:[1,0]
	v_pk_mov_b32 v[6:7], v[4:5], v[2:3] op_sel:[1,0]
	v_mov_b32_e32 v5, v3
	v_pk_add_f32 v[2:3], v[6:7], v[4:5]
	v_mul_f32_e32 v4, v94, v94
	v_mul_f32_e32 v5, v95, v95
	v_pk_add_f32 v[2:3], v[2:3], v[2:3] op_sel:[0,1] op_sel_hi:[1,0]
	v_mov_b32_e32 v1, v4
	v_mov_b32_e32 v3, v5
	s_waitcnt vmcnt(22)
	v_cvt_f32_f16_e32 v72, v96
	v_cvt_f32_f16_sdwa v73, v96 dst_sel:DWORD dst_unused:UNUSED_PAD src0_sel:WORD_1
	v_cvt_f32_f16_e32 v74, v97
	v_cvt_f32_f16_sdwa v75, v97 dst_sel:DWORD dst_unused:UNUSED_PAD src0_sel:WORD_1
	v_pk_add_f32 v[0:1], v[0:1], v[2:3]
	v_mul_f32_e32 v2, v121, v121
	v_mul_f32_e32 v4, v123, v123
	v_mul_f32_e32 v6, v92, v92
	v_mul_f32_e32 v7, v93, v93
	v_pk_fma_f32 v[2:3], v[120:121], v[120:121], v[2:3] op_sel_hi:[1,1,0]
	v_pk_fma_f32 v[4:5], v[122:123], v[122:123], v[4:5] op_sel_hi:[1,1,0]
	v_mov_b32_e32 v3, v6
	v_mov_b32_e32 v5, v7
	s_waitcnt vmcnt(20)
	v_cvt_f32_f16_sdwa v39, v106 dst_sel:DWORD dst_unused:UNUSED_PAD src0_sel:WORD_1
	v_cvt_f32_f16_e32 v38, v106
	v_pk_add_f32 v[2:3], v[2:3], v[4:5]
	v_pk_mul_f32 v[4:5], v[72:73], v[72:73]
	v_pk_add_f32 v[0:1], v[0:1], v[2:3]
	v_pk_mul_f32 v[2:3], v[74:75], v[74:75]
	v_cvt_f32_f16_sdwa v51, v98 dst_sel:DWORD dst_unused:UNUSED_PAD src0_sel:WORD_1
	v_cvt_f32_f16_sdwa v53, v99 dst_sel:DWORD dst_unused:UNUSED_PAD src0_sel:WORD_1
	v_pk_mov_b32 v[6:7], v[4:5], v[2:3] op_sel:[1,0]
	v_mov_b32_e32 v5, v3
	v_cvt_f32_f16_e32 v50, v98
	v_cvt_f32_f16_e32 v52, v99
	v_cvt_f32_f16_sdwa v37, v107 dst_sel:DWORD dst_unused:UNUSED_PAD src0_sel:WORD_1
	v_cvt_f32_f16_e32 v36, v107
	v_pk_add_f32 v[2:3], v[6:7], v[4:5]
	v_mul_f32_e32 v4, v38, v38
	v_mul_f32_e32 v5, v39, v39
	v_pk_add_f32 v[0:1], v[0:1], v[0:1] op_sel:[0,1] op_sel_hi:[1,0]
	v_pk_add_f32 v[2:3], v[2:3], v[2:3] op_sel:[0,1] op_sel_hi:[1,0]
	v_mov_b32_e32 v1, v4
	v_mov_b32_e32 v3, v5
	v_pk_add_f32 v[0:1], v[0:1], v[2:3]
	v_mul_f32_e32 v2, v51, v51
	v_mul_f32_e32 v4, v53, v53
	v_mul_f32_e32 v6, v36, v36
	v_mul_f32_e32 v7, v37, v37
	v_pk_fma_f32 v[2:3], v[50:51], v[50:51], v[2:3] op_sel_hi:[1,1,0]
	v_pk_fma_f32 v[4:5], v[52:53], v[52:53], v[4:5] op_sel_hi:[1,1,0]
	v_mov_b32_e32 v3, v6
	v_mov_b32_e32 v5, v7
	v_pk_add_f32 v[2:3], v[2:3], v[4:5]
	s_waitcnt vmcnt(19)
	v_cvt_f32_f16_sdwa v157, v128 dst_sel:DWORD dst_unused:UNUSED_PAD src0_sel:WORD_1
	v_pk_add_f32 v[0:1], v[0:1], v[2:3]
	s_waitcnt vmcnt(18)
	v_cvt_f32_f16_sdwa v155, v130 dst_sel:DWORD dst_unused:UNUSED_PAD src0_sel:WORD_1
	v_add_f32_e32 v0, v0, v1
	ds_bpermute_b32 v1, v45, v0
	v_cvt_f32_f16_sdwa v107, v129 dst_sel:DWORD dst_unused:UNUSED_PAD src0_sel:WORD_1
	v_cvt_f32_f16_e32 v156, v128
	v_cvt_f32_f16_sdwa v153, v131 dst_sel:DWORD dst_unused:UNUSED_PAD src0_sel:WORD_1
	v_cvt_f32_f16_e32 v154, v130
	s_waitcnt lgkmcnt(0)
	v_add_f32_e32 v0, v0, v1
	ds_bpermute_b32 v1, v55, v0
	v_cvt_f32_f16_e32 v106, v129
	v_cvt_f32_f16_e32 v152, v131
	s_waitcnt vmcnt(17)
	v_cvt_f32_f16_e32 v144, v146
	v_cvt_f32_f16_sdwa v145, v146 dst_sel:DWORD dst_unused:UNUSED_PAD src0_sel:WORD_1
	s_waitcnt lgkmcnt(0)
	v_add_f32_e32 v0, v0, v1
	ds_bpermute_b32 v1, v65, v0
	v_cvt_f32_f16_e32 v146, v147
	v_cvt_f32_f16_sdwa v147, v147 dst_sel:DWORD dst_unused:UNUSED_PAD src0_sel:WORD_1
	v_mov_b32_e32 v2, v157
	v_mov_b32_e32 v3, v155
	s_waitcnt lgkmcnt(0)
	v_add_f32_e32 v0, v0, v1
	ds_bpermute_b32 v1, v67, v0
	v_pk_mul_f32 v[2:3], v[2:3], v[2:3]
	v_mov_b32_e32 v4, v107
	v_mov_b32_e32 v5, v153
	v_pk_mul_f32 v[4:5], v[4:5], v[4:5]
	s_waitcnt lgkmcnt(0)
	v_add_f32_e32 v0, v0, v1
	ds_bpermute_b32 v1, v173, v0
	s_waitcnt vmcnt(15)
	v_cvt_f32_f16_sdwa v99, v166 dst_sel:DWORD dst_unused:UNUSED_PAD src0_sel:WORD_1
	v_cvt_f32_f16_e32 v98, v166
	v_cvt_f32_f16_sdwa v129, v164 dst_sel:DWORD dst_unused:UNUSED_PAD src0_sel:WORD_1
	v_cvt_f32_f16_sdwa v131, v165 dst_sel:DWORD dst_unused:UNUSED_PAD src0_sel:WORD_1
	s_waitcnt lgkmcnt(0)
	v_add_f32_e32 v0, v0, v1
	ds_bpermute_b32 v1, v174, v0
	v_cvt_f32_f16_e32 v128, v164
	v_cvt_f32_f16_e32 v130, v165
	v_cvt_f32_f16_sdwa v97, v167 dst_sel:DWORD dst_unused:UNUSED_PAD src0_sel:WORD_1
	v_cvt_f32_f16_e32 v96, v167
	s_waitcnt lgkmcnt(0)
	v_add_f32_e32 v0, v0, v1
	v_fmamk_f32 v0, v0, 0x3a000000, v232
	v_rsq_f32_e32 v64, v0
	v_mov_b32_e32 v0, v156
	v_mov_b32_e32 v1, v154
	v_pk_fma_f32 v[0:1], v[0:1], v[0:1], v[2:3]
	v_mov_b32_e32 v2, v106
	v_mov_b32_e32 v3, v152
	v_pk_fma_f32 v[2:3], v[2:3], v[2:3], v[4:5]
	v_pk_mul_f32 v[4:5], v[144:145], v[144:145]
	v_pk_add_f32 v[0:1], v[0:1], v[2:3]
	v_pk_mul_f32 v[2:3], v[146:147], v[146:147]
	v_pk_add_f32 v[0:1], v[0:1], v[0:1] op_sel:[0,1] op_sel_hi:[1,0]
	v_pk_mov_b32 v[6:7], v[4:5], v[2:3] op_sel:[1,0]
	v_mov_b32_e32 v5, v3
	v_pk_add_f32 v[2:3], v[6:7], v[4:5]
	v_mul_f32_e32 v4, v98, v98
	v_mul_f32_e32 v5, v99, v99
	v_pk_add_f32 v[2:3], v[2:3], v[2:3] op_sel:[0,1] op_sel_hi:[1,0]
	v_mov_b32_e32 v1, v4
	v_mov_b32_e32 v3, v5
	s_waitcnt vmcnt(14)
	v_cvt_f32_f16_e32 v68, v168
	v_cvt_f32_f16_sdwa v69, v168 dst_sel:DWORD dst_unused:UNUSED_PAD src0_sel:WORD_1
	v_cvt_f32_f16_e32 v70, v169
	v_cvt_f32_f16_sdwa v71, v169 dst_sel:DWORD dst_unused:UNUSED_PAD src0_sel:WORD_1
	v_pk_add_f32 v[0:1], v[0:1], v[2:3]
	v_mul_f32_e32 v2, v129, v129
	v_mul_f32_e32 v4, v131, v131
	v_mul_f32_e32 v6, v96, v96
	v_mul_f32_e32 v7, v97, v97
	v_pk_fma_f32 v[2:3], v[128:129], v[128:129], v[2:3] op_sel_hi:[1,1,0]
	v_pk_fma_f32 v[4:5], v[130:131], v[130:131], v[4:5] op_sel_hi:[1,1,0]
	v_mov_b32_e32 v3, v6
	v_mov_b32_e32 v5, v7
	s_waitcnt vmcnt(12)
	v_cvt_f32_f16_sdwa v43, v176 dst_sel:DWORD dst_unused:UNUSED_PAD src0_sel:WORD_1
	v_cvt_f32_f16_e32 v42, v176
	v_pk_add_f32 v[2:3], v[2:3], v[4:5]
	v_pk_mul_f32 v[4:5], v[68:69], v[68:69]
	v_pk_add_f32 v[0:1], v[0:1], v[2:3]
	v_pk_mul_f32 v[2:3], v[70:71], v[70:71]
	v_cvt_f32_f16_sdwa v47, v170 dst_sel:DWORD dst_unused:UNUSED_PAD src0_sel:WORD_1
	v_cvt_f32_f16_sdwa v49, v171 dst_sel:DWORD dst_unused:UNUSED_PAD src0_sel:WORD_1
	v_pk_mov_b32 v[6:7], v[4:5], v[2:3] op_sel:[1,0]
	v_mov_b32_e32 v5, v3
	v_cvt_f32_f16_e32 v46, v170
	v_cvt_f32_f16_e32 v48, v171
	v_cvt_f32_f16_sdwa v41, v177 dst_sel:DWORD dst_unused:UNUSED_PAD src0_sel:WORD_1
	v_cvt_f32_f16_e32 v40, v177
	v_pk_add_f32 v[2:3], v[6:7], v[4:5]
	v_mul_f32_e32 v4, v42, v42
	v_mul_f32_e32 v5, v43, v43
	v_pk_add_f32 v[0:1], v[0:1], v[0:1] op_sel:[0,1] op_sel_hi:[1,0]
	v_pk_add_f32 v[2:3], v[2:3], v[2:3] op_sel:[0,1] op_sel_hi:[1,0]
	v_mov_b32_e32 v1, v4
	v_mov_b32_e32 v3, v5
	v_pk_add_f32 v[0:1], v[0:1], v[2:3]
	v_mul_f32_e32 v2, v47, v47
	v_mul_f32_e32 v4, v49, v49
	v_mul_f32_e32 v6, v40, v40
	v_mul_f32_e32 v7, v41, v41
	v_pk_fma_f32 v[2:3], v[46:47], v[46:47], v[2:3] op_sel_hi:[1,1,0]
	v_pk_fma_f32 v[4:5], v[48:49], v[48:49], v[4:5] op_sel_hi:[1,1,0]
	v_mov_b32_e32 v3, v6
	v_mov_b32_e32 v5, v7
	v_pk_add_f32 v[2:3], v[2:3], v[4:5]
	v_mad_i64_i32 v[166:167], s[52:53], s5, v237, v[22:23]
	v_pk_add_f32 v[0:1], v[0:1], v[2:3]
	v_mad_i64_i32 v[164:165], s[52:53], s5, v237, v[24:25]
	v_add_f32_e32 v0, v0, v1
	ds_bpermute_b32 v1, v45, v0
	v_pk_mul_f32 v[100:101], v[44:45], v[100:101] op_sel_hi:[0,1]
	v_pk_mul_f32 v[162:163], v[44:45], v[162:163] op_sel_hi:[0,1]
	v_pk_mul_f32 v[102:103], v[54:55], v[102:103] op_sel_hi:[0,1]
	v_pk_mul_f32 v[160:161], v[54:55], v[160:161] op_sel_hi:[0,1]
	s_waitcnt lgkmcnt(0)
	v_add_f32_e32 v0, v0, v1
	ds_bpermute_b32 v1, v55, v0
	v_pk_mul_f32 v[104:105], v[64:65], v[104:105] op_sel_hi:[0,1]
	v_pk_mul_f32 v[158:159], v[64:65], v[158:159] op_sel_hi:[0,1]
	v_pk_mul_f32 v[132:133], v[44:45], v[132:133] op_sel_hi:[0,1]
	v_pk_mul_f32 v[134:135], v[44:45], v[134:135] op_sel_hi:[0,1]
	s_waitcnt lgkmcnt(0)
	v_add_f32_e32 v0, v0, v1
	ds_bpermute_b32 v1, v65, v0
	v_pk_mul_f32 v[118:119], v[44:45], v[118:119] op_sel_hi:[0,1]
	v_pk_mul_f32 v[116:117], v[44:45], v[116:117] op_sel_hi:[0,1]
	v_pk_mul_f32 v[110:111], v[44:45], v[110:111] op_sel_hi:[0,1]
	v_pk_mul_f32 v[108:109], v[44:45], v[108:109] op_sel_hi:[0,1]
	s_waitcnt lgkmcnt(0)
	v_add_f32_e32 v0, v0, v1
	ds_bpermute_b32 v1, v67, v0
	v_pk_mul_f32 v[86:87], v[44:45], v[86:87] op_sel_hi:[0,1]
	v_pk_mul_f32 v[84:85], v[44:45], v[84:85] op_sel_hi:[0,1]
	v_pk_mul_f32 v[82:83], v[44:45], v[82:83] op_sel_hi:[0,1]
	v_pk_mul_f32 v[80:81], v[44:45], v[80:81] op_sel_hi:[0,1]
	s_waitcnt lgkmcnt(0)
	v_add_f32_e32 v0, v0, v1
	ds_bpermute_b32 v1, v173, v0
	v_pk_mul_f32 v[78:79], v[54:55], v[78:79] op_sel_hi:[0,1]
	v_pk_mul_f32 v[76:77], v[54:55], v[76:77] op_sel_hi:[0,1]
	v_pk_mul_f32 v[74:75], v[64:65], v[74:75] op_sel_hi:[0,1]
	v_pk_mul_f32 v[72:73], v[64:65], v[72:73] op_sel_hi:[0,1]
	s_waitcnt lgkmcnt(0)
	v_add_f32_e32 v0, v0, v1
	ds_bpermute_b32 v1, v174, v0
	v_pk_mul_f32 v[58:59], v[44:45], v[58:59] op_sel_hi:[0,1]
	v_pk_mul_f32 v[56:57], v[44:45], v[56:57] op_sel_hi:[0,1]
	v_pk_mul_f32 v[52:53], v[64:65], v[52:53] op_sel_hi:[0,1]
	v_pk_mul_f32 v[50:51], v[64:65], v[50:51] op_sel_hi:[0,1]
	s_waitcnt lgkmcnt(0)
	v_add_f32_e32 v0, v0, v1
	v_fmamk_f32 v0, v0, 0x3a000000, v232
	v_rsq_f32_e32 v66, v0
	v_pk_mul_f32 v[28:29], v[44:45], v[28:29] op_sel_hi:[0,1]
	v_pk_mul_f32 v[30:31], v[44:45], v[30:31] op_sel_hi:[0,1]
	v_pk_mul_f32 v[106:107], v[66:67], v[106:107] op_sel_hi:[0,1]
	v_pk_mul_f32 v[156:157], v[66:67], v[156:157] op_sel_hi:[0,1]
	v_pk_mul_f32 v[70:71], v[66:67], v[70:71] op_sel_hi:[0,1]
	v_pk_mul_f32 v[68:69], v[66:67], v[68:69] op_sel_hi:[0,1]
	v_pk_mul_f32 v[48:49], v[66:67], v[48:49] op_sel_hi:[0,1]
	v_pk_mul_f32 v[46:47], v[66:67], v[46:47] op_sel_hi:[0,1]
	s_waitcnt vmcnt(9)
	v_pk_mul_f32 v[162:163], v[162:163], v[180:181]
	v_pk_mul_f32 v[100:101], v[100:101], v[182:183]
	v_pk_add_f32 v[168:169], v[190:191], 1.0 op_sel_hi:[1,0]
	v_pk_add_f32 v[170:171], v[188:189], 1.0 op_sel_hi:[1,0]
	v_pk_fma_f32 v[100:101], v[100:101], v[168:169], v[186:187]
	v_pk_fma_f32 v[162:163], v[162:163], v[170:171], v[184:185]
	v_pk_mul_f32 v[160:161], v[160:161], v[180:181]
	v_cvt_pk_bf16_f32 v162, v162, v163
	v_cvt_pk_bf16_f32 v163, v100, v101
	v_lshl_add_u64 v[100:101], s[14:15], 0, v[18:19]
	v_pk_mul_f32 v[102:103], v[102:103], v[182:183]
	v_add_co_u32_e32 v100, vcc, s30, v100
	v_pk_fma_f32 v[102:103], v[102:103], v[168:169], v[186:187]
	v_pk_fma_f32 v[160:161], v[160:161], v[170:171], v[184:185]
	v_addc_co_u32_e32 v101, vcc, 0, v101, vcc
	v_cvt_pk_bf16_f32 v160, v160, v161
	v_cvt_pk_bf16_f32 v161, v102, v103
	v_lshl_add_u64 v[102:103], s[8:9], 0, v[18:19]
	v_pk_mul_f32 v[158:159], v[180:181], v[158:159]
	v_pk_mul_f32 v[104:105], v[182:183], v[104:105]
	v_pk_mul_f32 v[180:181], v[180:181], v[156:157]
	v_pk_mul_f32 v[182:183], v[182:183], v[106:107]
	v_add_co_u32_e32 v102, vcc, s30, v102
	v_pk_fma_f32 v[104:105], v[104:105], v[168:169], v[186:187]
	v_pk_fma_f32 v[158:159], v[158:159], v[170:171], v[184:185]
	v_pk_fma_f32 v[186:187], v[168:169], v[182:183], v[186:187]
	v_pk_fma_f32 v[184:185], v[170:171], v[180:181], v[184:185]
	v_addc_co_u32_e32 v103, vcc, 0, v103, vcc
	v_cvt_pk_bf16_f32 v158, v158, v159
	v_cvt_pk_bf16_f32 v159, v104, v105
	v_lshl_add_u64 v[104:105], v[26:27], 0, s[18:19]
	v_cvt_pk_bf16_f32 v184, v184, v185
	v_cvt_pk_bf16_f32 v185, v186, v187
	v_lshl_add_u64 v[106:107], v[26:27], 0, s[22:23]
	global_store_dwordx2 v[100:101], v[162:163], off
	global_store_dwordx2 v[102:103], v[160:161], off
	global_store_dwordx2 v[104:105], v[158:159], off
	global_store_dwordx2 v[106:107], v[184:185], off
	global_load_dwordx4 v[180:183], v[10:11], off
	global_load_dwordx4 v[184:187], v[252:253], off
	global_load_dwordx4 v[188:191], v[250:251], off
	s_nop 0
	s_cselect_b64 s[18:19], -1, 0
	s_add_u32 s8, s8, s10
	s_addc_u32 s9, s9, s11
	s_add_u32 s12, s12, s10
	s_addc_u32 s13, s13, s11
	s_add_u32 s14, s14, s10
	s_addc_u32 s15, s15, s11
	s_add_u32 s16, s16, s10
	s_addc_u32 s17, s17, s11
	s_waitcnt vmcnt(13)
	v_pk_mul_f32 v[134:135], v[134:135], v[196:197]
	v_pk_mul_f32 v[132:133], v[132:133], v[198:199]
	v_pk_add_f32 v[206:207], v[206:207], 1.0 op_sel_hi:[1,0]
	v_pk_add_f32 v[204:205], v[204:205], 1.0 op_sel_hi:[1,0]
	v_pk_fma_f32 v[132:133], v[132:133], v[206:207], v[202:203]
	v_pk_fma_f32 v[134:135], v[134:135], v[204:205], v[200:201]
	s_nop 0
	v_cvt_pk_bf16_f32 v134, v134, v135
	v_cvt_pk_bf16_f32 v135, v132, v133
	global_store_dwordx2 v[100:101], v[134:135], off offset:512
	v_pk_mul_f32 v[132:133], v[54:55], v[140:141] op_sel_hi:[0,1]
	v_pk_mul_f32 v[134:135], v[54:55], v[142:143] op_sel_hi:[0,1]
	v_pk_mul_f32 v[134:135], v[134:135], v[196:197]
	v_pk_mul_f32 v[132:133], v[132:133], v[198:199]
	v_pk_fma_f32 v[134:135], v[134:135], v[204:205], v[200:201]
	v_pk_fma_f32 v[132:133], v[132:133], v[206:207], v[202:203]
	v_cvt_pk_bf16_f32 v134, v134, v135
	v_cvt_pk_bf16_f32 v135, v132, v133
	global_store_dwordx2 v[102:103], v[134:135], off offset:512
	v_pk_mul_f32 v[132:133], v[64:65], v[148:149] op_sel_hi:[0,1]
	v_pk_mul_f32 v[134:135], v[64:65], v[150:151] op_sel_hi:[0,1]
	v_pk_mul_f32 v[134:135], v[134:135], v[196:197]
	v_pk_mul_f32 v[132:133], v[132:133], v[198:199]
	v_pk_fma_f32 v[134:135], v[134:135], v[204:205], v[200:201]
	v_pk_fma_f32 v[132:133], v[132:133], v[206:207], v[202:203]
	v_cvt_pk_bf16_f32 v134, v134, v135
	v_cvt_pk_bf16_f32 v135, v132, v133
	global_store_dwordx2 v[104:105], v[134:135], off offset:512
	v_pk_mul_f32 v[132:133], v[66:67], v[152:153] op_sel_hi:[0,1]
	v_pk_mul_f32 v[134:135], v[66:67], v[154:155] op_sel_hi:[0,1]
	v_pk_mul_f32 v[196:197], v[196:197], v[134:135]
	v_pk_mul_f32 v[198:199], v[198:199], v[132:133]
	v_pk_fma_f32 v[196:197], v[196:197], v[204:205], v[200:201]
	v_pk_fma_f32 v[198:199], v[198:199], v[206:207], v[202:203]
	v_cvt_pk_bf16_f32 v196, v196, v197
	v_cvt_pk_bf16_f32 v197, v198, v199
	global_store_dwordx2 v[106:107], v[196:197], off offset:512
	global_load_dwordx4 v[196:199], v[12:13], off
	global_load_dwordx4 v[200:203], v[250:251], off offset:1024
	global_load_dwordx4 v[204:207], v[252:253], off offset:1024
	s_nop 0
	s_waitcnt vmcnt(17)
	v_pk_mul_f32 v[116:117], v[116:117], v[208:209]
	v_pk_mul_f32 v[118:119], v[118:119], v[210:211]
	v_pk_add_f32 v[220:221], v[220:221], 1.0 op_sel_hi:[1,0]
	v_pk_add_f32 v[218:219], v[218:219], 1.0 op_sel_hi:[1,0]
	v_pk_fma_f32 v[118:119], v[118:119], v[220:221], v[214:215]
	v_pk_fma_f32 v[116:117], v[116:117], v[218:219], v[212:213]
	s_nop 0
	v_cvt_pk_bf16_f32 v116, v116, v117
	v_cvt_pk_bf16_f32 v117, v118, v119
	global_store_dwordx2 v[100:101], v[116:117], off offset:1024
	v_pk_mul_f32 v[116:117], v[54:55], v[126:127] op_sel_hi:[0,1]
	v_pk_mul_f32 v[118:119], v[54:55], v[124:125] op_sel_hi:[0,1]
	v_pk_mul_f32 v[118:119], v[118:119], v[208:209]
	v_pk_mul_f32 v[116:117], v[116:117], v[210:211]
	v_pk_fma_f32 v[118:119], v[118:119], v[218:219], v[212:213]
	v_pk_fma_f32 v[116:117], v[116:117], v[220:221], v[214:215]
	v_cvt_pk_bf16_f32 v118, v118, v119
	v_cvt_pk_bf16_f32 v119, v116, v117
	global_store_dwordx2 v[102:103], v[118:119], off offset:1024
	v_pk_mul_f32 v[116:117], v[64:65], v[138:139] op_sel_hi:[0,1]
	v_pk_mul_f32 v[118:119], v[64:65], v[136:137] op_sel_hi:[0,1]
	v_pk_mul_f32 v[118:119], v[118:119], v[208:209]
	v_pk_mul_f32 v[116:117], v[116:117], v[210:211]
	v_pk_fma_f32 v[118:119], v[118:119], v[218:219], v[212:213]
	v_pk_fma_f32 v[116:117], v[116:117], v[220:221], v[214:215]
	v_cvt_pk_bf16_f32 v118, v118, v119
	v_cvt_pk_bf16_f32 v119, v116, v117
	global_store_dwordx2 v[104:105], v[118:119], off offset:1024
	v_pk_mul_f32 v[116:117], v[66:67], v[146:147] op_sel_hi:[0,1]
	v_pk_mul_f32 v[118:119], v[66:67], v[144:145] op_sel_hi:[0,1]
	v_pk_mul_f32 v[208:209], v[118:119], v[208:209]
	v_pk_mul_f32 v[210:211], v[116:117], v[210:211]
	v_pk_fma_f32 v[208:209], v[208:209], v[218:219], v[212:213]
	v_pk_fma_f32 v[210:211], v[210:211], v[220:221], v[214:215]
	v_cvt_pk_bf16_f32 v208, v208, v209
	v_cvt_pk_bf16_f32 v209, v210, v211
	global_store_dwordx2 v[106:107], v[208:209], off offset:1024
	global_load_dwordx4 v[208:211], v[14:15], off
	global_load_dwordx4 v[212:215], v[250:251], off offset:2048
	global_load_dwordx4 v[218:221], v[252:253], off offset:2048
	s_nop 0
	s_waitcnt vmcnt(21)
	v_pk_mul_f32 v[108:109], v[108:109], v[222:223]
	v_pk_mul_f32 v[110:111], v[110:111], v[224:225]
	v_pk_add_f32 v[244:245], v[244:245], 1.0 op_sel_hi:[1,0]
	v_pk_add_f32 v[242:243], v[242:243], 1.0 op_sel_hi:[1,0]
	v_pk_fma_f32 v[110:111], v[110:111], v[244:245], v[228:229]
	v_pk_fma_f32 v[108:109], v[108:109], v[242:243], v[226:227]
	s_nop 0
	v_cvt_pk_bf16_f32 v108, v108, v109
	v_cvt_pk_bf16_f32 v109, v110, v111
	global_store_dwordx2 v[100:101], v[108:109], off offset:1536
	v_pk_mul_f32 v[108:109], v[54:55], v[114:115] op_sel_hi:[0,1]
	v_pk_mul_f32 v[110:111], v[54:55], v[112:113] op_sel_hi:[0,1]
	v_pk_mul_f32 v[110:111], v[110:111], v[222:223]
	v_pk_mul_f32 v[108:109], v[108:109], v[224:225]
	v_pk_fma_f32 v[110:111], v[110:111], v[242:243], v[226:227]
	v_pk_fma_f32 v[108:109], v[108:109], v[244:245], v[228:229]
	v_cvt_pk_bf16_f32 v110, v110, v111
	v_cvt_pk_bf16_f32 v111, v108, v109
	global_store_dwordx2 v[102:103], v[110:111], off offset:1536
	v_pk_mul_f32 v[108:109], v[64:65], v[122:123] op_sel_hi:[0,1]
	v_pk_mul_f32 v[110:111], v[64:65], v[120:121] op_sel_hi:[0,1]
	v_pk_mul_f32 v[110:111], v[110:111], v[222:223]
	v_pk_mul_f32 v[108:109], v[108:109], v[224:225]
	v_pk_fma_f32 v[110:111], v[110:111], v[242:243], v[226:227]
	v_pk_fma_f32 v[108:109], v[108:109], v[244:245], v[228:229]
	v_cvt_pk_bf16_f32 v110, v110, v111
	v_cvt_pk_bf16_f32 v111, v108, v109
	global_store_dwordx2 v[104:105], v[110:111], off offset:1536
	v_pk_mul_f32 v[108:109], v[66:67], v[130:131] op_sel_hi:[0,1]
	v_pk_mul_f32 v[110:111], v[66:67], v[128:129] op_sel_hi:[0,1]
	v_pk_mul_f32 v[222:223], v[110:111], v[222:223]
	v_pk_mul_f32 v[224:225], v[108:109], v[224:225]
	v_add_co_u32_e32 v108, vcc, s77, v166
	v_pk_fma_f32 v[224:225], v[224:225], v[244:245], v[228:229]
	v_pk_fma_f32 v[222:223], v[222:223], v[242:243], v[226:227]
	v_addc_co_u32_e32 v109, vcc, 0, v167, vcc
	v_cvt_pk_bf16_f32 v222, v222, v223
	v_cvt_pk_bf16_f32 v223, v224, v225
	v_add_co_u32_e32 v110, vcc, s77, v164
	global_store_dwordx2 v[106:107], v[222:223], off offset:1536
	global_load_dwordx4 v[222:225], v[16:17], off
	global_load_dwordx4 v[226:229], v[250:251], off offset:3072
	global_load_dwordx4 v[242:245], v[252:253], off offset:3072
	s_nop 0
	v_addc_co_u32_e32 v111, vcc, 0, v165, vcc
	v_subrev_co_u32_e32 v175, vcc, 1, v175
	s_waitcnt vmcnt(21)
	v_pk_mul_f32 v[84:85], v[84:85], v[180:181]
	v_pk_add_f32 v[112:113], v[186:187], 1.0 op_sel_hi:[1,0]
	v_pk_add_f32 v[184:185], v[184:185], 1.0 op_sel_hi:[1,0]
	v_pk_mul_f32 v[86:87], v[86:87], v[182:183]
	v_pk_fma_f32 v[84:85], v[84:85], v[184:185], v[188:189]
	v_pk_fma_f32 v[86:87], v[86:87], v[112:113], v[190:191]
	v_cvt_pk_bf16_f32 v84, v84, v85
	v_cvt_pk_bf16_f32 v85, v86, v87
	global_store_dwordx2 v[100:101], v[84:85], off offset:2048
	v_pk_mul_f32 v[84:85], v[54:55], v[88:89] op_sel_hi:[0,1]
	v_pk_mul_f32 v[86:87], v[54:55], v[90:91] op_sel_hi:[0,1]
	v_pk_mul_f32 v[86:87], v[86:87], v[180:181]
	v_pk_mul_f32 v[84:85], v[84:85], v[182:183]
	v_pk_fma_f32 v[86:87], v[86:87], v[184:185], v[188:189]
	v_pk_fma_f32 v[84:85], v[84:85], v[112:113], v[190:191]
	v_cvt_pk_bf16_f32 v86, v86, v87
	v_cvt_pk_bf16_f32 v87, v84, v85
	global_store_dwordx2 v[102:103], v[86:87], off offset:2048
	v_pk_mul_f32 v[84:85], v[64:65], v[92:93] op_sel_hi:[0,1]
	v_pk_mul_f32 v[86:87], v[64:65], v[94:95] op_sel_hi:[0,1]
	v_pk_mul_f32 v[86:87], v[86:87], v[180:181]
	v_pk_mul_f32 v[84:85], v[84:85], v[182:183]
	v_pk_fma_f32 v[86:87], v[86:87], v[184:185], v[188:189]
	v_pk_fma_f32 v[84:85], v[84:85], v[112:113], v[190:191]
	v_cvt_pk_bf16_f32 v86, v86, v87
	v_cvt_pk_bf16_f32 v87, v84, v85
	global_store_dwordx2 v[104:105], v[86:87], off offset:2048
	v_pk_mul_f32 v[84:85], v[66:67], v[96:97] op_sel_hi:[0,1]
	v_pk_mul_f32 v[86:87], v[66:67], v[98:99] op_sel_hi:[0,1]
	v_pk_mul_f32 v[180:181], v[86:87], v[180:181]
	v_pk_mul_f32 v[182:183], v[84:85], v[182:183]
	v_pk_fma_f32 v[180:181], v[180:181], v[184:185], v[188:189]
	v_pk_fma_f32 v[182:183], v[182:183], v[112:113], v[190:191]
	v_cvt_pk_bf16_f32 v180, v180, v181
	v_cvt_pk_bf16_f32 v181, v182, v183
	global_store_dwordx2 v[106:107], v[180:181], off offset:2048
	s_nop 0
	s_waitcnt vmcnt(18)
	v_pk_mul_f32 v[80:81], v[80:81], v[196:197]
	v_pk_mul_f32 v[82:83], v[82:83], v[198:199]
	v_pk_add_f32 v[84:85], v[206:207], 1.0 op_sel_hi:[1,0]
	v_pk_add_f32 v[204:205], v[204:205], 1.0 op_sel_hi:[1,0]
	v_pk_mul_f32 v[76:77], v[76:77], v[196:197]
	v_pk_mul_f32 v[78:79], v[78:79], v[198:199]
	v_pk_mul_f32 v[72:73], v[72:73], v[196:197]
	v_pk_mul_f32 v[74:75], v[74:75], v[198:199]
	v_pk_mul_f32 v[196:197], v[68:69], v[196:197]
	v_pk_mul_f32 v[198:199], v[70:71], v[198:199]
	v_pk_fma_f32 v[82:83], v[82:83], v[84:85], v[202:203]
	v_pk_fma_f32 v[80:81], v[80:81], v[204:205], v[200:201]
	v_pk_fma_f32 v[78:79], v[78:79], v[84:85], v[202:203]
	v_pk_fma_f32 v[76:77], v[76:77], v[204:205], v[200:201]
	v_pk_fma_f32 v[74:75], v[74:75], v[84:85], v[202:203]
	v_pk_fma_f32 v[72:73], v[72:73], v[204:205], v[200:201]
	v_pk_fma_f32 v[202:203], v[198:199], v[84:85], v[202:203]
	v_pk_fma_f32 v[200:201], v[196:197], v[204:205], v[200:201]
	v_cvt_pk_bf16_f32 v80, v80, v81
	v_cvt_pk_bf16_f32 v81, v82, v83
	v_cvt_pk_bf16_f32 v76, v76, v77
	v_cvt_pk_bf16_f32 v77, v78, v79
	v_cvt_pk_bf16_f32 v72, v72, v73
	v_cvt_pk_bf16_f32 v73, v74, v75
	v_cvt_pk_bf16_f32 v200, v200, v201
	v_cvt_pk_bf16_f32 v201, v202, v203
	global_store_dwordx2 v[100:101], v[80:81], off offset:2560
	global_store_dwordx2 v[102:103], v[76:77], off offset:2560
	global_store_dwordx2 v[104:105], v[72:73], off offset:2560
	global_store_dwordx2 v[106:107], v[200:201], off offset:2560
	s_nop 0
	s_waitcnt vmcnt(15)
	v_pk_mul_f32 v[56:57], v[56:57], v[208:209]
	v_pk_mul_f32 v[58:59], v[58:59], v[210:211]
	v_pk_add_f32 v[220:221], v[220:221], 1.0 op_sel_hi:[1,0]
	v_pk_add_f32 v[218:219], v[218:219], 1.0 op_sel_hi:[1,0]
	v_pk_fma_f32 v[58:59], v[58:59], v[220:221], v[214:215]
	v_pk_fma_f32 v[56:57], v[56:57], v[218:219], v[212:213]
	v_pk_mul_f32 v[50:51], v[50:51], v[208:209]
	v_cvt_pk_bf16_f32 v56, v56, v57
	v_cvt_pk_bf16_f32 v57, v58, v59
	global_store_dwordx2 v[100:101], v[56:57], off offset:3072
	v_pk_mul_f32 v[56:57], v[54:55], v[62:63] op_sel_hi:[0,1]
	v_pk_mul_f32 v[58:59], v[54:55], v[60:61] op_sel_hi:[0,1]
	v_pk_mul_f32 v[58:59], v[58:59], v[208:209]
	v_pk_mul_f32 v[56:57], v[56:57], v[210:211]
	v_pk_mul_f32 v[52:53], v[52:53], v[210:211]
	v_pk_mul_f32 v[208:209], v[46:47], v[208:209]
	v_pk_mul_f32 v[210:211], v[48:49], v[210:211]
	v_pk_fma_f32 v[56:57], v[56:57], v[220:221], v[214:215]
	v_pk_fma_f32 v[58:59], v[58:59], v[218:219], v[212:213]
	v_pk_fma_f32 v[52:53], v[52:53], v[220:221], v[214:215]
	v_pk_fma_f32 v[50:51], v[50:51], v[218:219], v[212:213]
	v_pk_fma_f32 v[210:211], v[210:211], v[220:221], v[214:215]
	v_pk_fma_f32 v[208:209], v[208:209], v[218:219], v[212:213]
	v_cvt_pk_bf16_f32 v58, v58, v59
	v_cvt_pk_bf16_f32 v59, v56, v57
	v_cvt_pk_bf16_f32 v50, v50, v51
	v_cvt_pk_bf16_f32 v51, v52, v53
	v_cvt_pk_bf16_f32 v208, v208, v209
	v_cvt_pk_bf16_f32 v209, v210, v211
	global_store_dwordx2 v[102:103], v[58:59], off offset:3072
	global_store_dwordx2 v[104:105], v[50:51], off offset:3072
	global_store_dwordx2 v[106:107], v[208:209], off offset:3072
	s_nop 0
	s_waitcnt vmcnt(12)
	v_pk_mul_f32 v[30:31], v[30:31], v[222:223]
	v_pk_mul_f32 v[28:29], v[28:29], v[224:225]
	v_pk_add_f32 v[244:245], v[244:245], 1.0 op_sel_hi:[1,0]
	v_pk_add_f32 v[242:243], v[242:243], 1.0 op_sel_hi:[1,0]
	v_pk_fma_f32 v[28:29], v[28:29], v[244:245], v[228:229]
	v_pk_fma_f32 v[30:31], v[30:31], v[242:243], v[226:227]
	s_nop 0
	v_cvt_pk_bf16_f32 v30, v30, v31
	v_cvt_pk_bf16_f32 v31, v28, v29
	global_store_dwordx2 v[100:101], v[30:31], off offset:3584
	v_pk_mul_f32 v[28:29], v[54:55], v[32:33] op_sel_hi:[0,1]
	v_pk_mul_f32 v[30:31], v[54:55], v[34:35] op_sel_hi:[0,1]
	v_pk_mul_f32 v[30:31], v[30:31], v[222:223]
	v_pk_mul_f32 v[28:29], v[28:29], v[224:225]
	v_pk_fma_f32 v[30:31], v[30:31], v[242:243], v[226:227]
	v_pk_fma_f32 v[28:29], v[28:29], v[244:245], v[228:229]
	v_cvt_pk_bf16_f32 v30, v30, v31
	v_cvt_pk_bf16_f32 v31, v28, v29
	global_store_dwordx2 v[102:103], v[30:31], off offset:3584
	v_pk_mul_f32 v[28:29], v[64:65], v[36:37] op_sel_hi:[0,1]
	v_pk_mul_f32 v[30:31], v[64:65], v[38:39] op_sel_hi:[0,1]
	v_pk_mul_f32 v[30:31], v[30:31], v[222:223]
	v_pk_mul_f32 v[28:29], v[28:29], v[224:225]
	v_pk_fma_f32 v[30:31], v[30:31], v[242:243], v[226:227]
	v_pk_fma_f32 v[28:29], v[28:29], v[244:245], v[228:229]
	v_cvt_pk_bf16_f32 v30, v30, v31
	v_cvt_pk_bf16_f32 v31, v28, v29
	global_store_dwordx2 v[104:105], v[30:31], off offset:3584
	v_pk_mul_f32 v[28:29], v[66:67], v[40:41] op_sel_hi:[0,1]
	v_pk_mul_f32 v[30:31], v[66:67], v[42:43] op_sel_hi:[0,1]
	v_pk_mul_f32 v[222:223], v[30:31], v[222:223]
	v_pk_mul_f32 v[224:225], v[28:29], v[224:225]
	v_pk_fma_f32 v[222:223], v[222:223], v[242:243], v[226:227]
	v_pk_fma_f32 v[224:225], v[224:225], v[244:245], v[228:229]
	v_cvt_pk_bf16_f32 v222, v222, v223
	v_cvt_pk_bf16_f32 v223, v224, v225
	global_store_dwordx2 v[106:107], v[222:223], off offset:3584
	v_cndmask_b32_e64 v0, 0, 1, vcc
	v_cndmask_b32_e64 v1, 0, 1, s[18:19]
	v_cndmask_b32_e64 v0, v1, v0, s[2:3]
	v_and_b32_e32 v0, 1, v0
	v_cmp_eq_u32_e32 vcc, 1, v0
	s_cbranch_vccnz .LBB0_1793
